# GEMM K-loop variant: DMA issue threaded through MFMA groups 1-2
# baseline (speedup 1.0000x reference)
.LBB0_212:
	s_add_i32 s1, s0, 0x10000
	s_and_b32 s11, s1, 0x10000
	s_waitcnt vmcnt(0)
	s_barrier
	s_and_b32 s0, s0, 0x10000
	s_add_i32 s0, s0, 0
	v_add_u32_e32 v155, s0, v153
	v_add_u32_e32 v164, v155, v151
	ds_read_b128 v[156:159], v164
	ds_read_b128 v[160:163], v164 offset:2048
	ds_read_b128 v[178:181], v164 offset:4096
	ds_read_b128 v[182:185], v164 offset:6144
	v_add_u32_e32 v249, v155, v150
	v_add_u32_e32 v164, s0, v154
	v_add_u32_e32 v165, v164, v151
	ds_read_b128 v[186:189], v165 offset:32768
	ds_read_b128 v[192:195], v165 offset:34816
	ds_read_b128 v[198:201], v165 offset:36864
	ds_read_b128 v[204:207], v165 offset:38912
	v_add_u32_e32 v248, v164, v150
	s_waitcnt lgkmcnt(0)
	v_mfma_f32_16x16x32_bf16 v[124:127], v[156:159], v[186:189], v[124:127]
	ds_read_b128 v[224:227], v165 offset:40960
	v_mfma_f32_16x16x32_bf16 v[120:123], v[156:159], v[192:195], v[120:123]
	ds_read_b128 v[228:231], v165 offset:43008
	v_mfma_f32_16x16x32_bf16 v[116:119], v[156:159], v[198:201], v[116:119]
	ds_read_b128 v[232:235], v165 offset:45056
	v_mfma_f32_16x16x32_bf16 v[112:115], v[156:159], v[204:207], v[112:115]
	ds_read_b128 v[236:239], v165 offset:47104
	v_mfma_f32_16x16x32_bf16 v[104:107], v[160:163], v[186:189], v[104:107]
	ds_read_b128 v[208:211], v249
	v_mfma_f32_16x16x32_bf16 v[96:99], v[160:163], v[192:195], v[96:99]
	ds_read_b128 v[212:215], v249 offset:2048
	v_mfma_f32_16x16x32_bf16 v[88:91], v[160:163], v[198:201], v[88:91]
	ds_read_b128 v[216:219], v249 offset:4096
	v_mfma_f32_16x16x32_bf16 v[80:83], v[160:163], v[204:207], v[80:83]
	ds_read_b128 v[220:223], v249 offset:6144
	v_mfma_f32_16x16x32_bf16 v[72:75], v[178:181], v[186:189], v[72:75]
	v_mfma_f32_16x16x32_bf16 v[64:67], v[178:181], v[192:195], v[64:67]
	v_mfma_f32_16x16x32_bf16 v[56:59], v[178:181], v[198:201], v[56:59]
	v_mfma_f32_16x16x32_bf16 v[48:51], v[178:181], v[204:207], v[48:51]
	v_mfma_f32_16x16x32_bf16 v[40:43], v[182:185], v[186:189], v[40:43]
	v_mfma_f32_16x16x32_bf16 v[32:35], v[182:185], v[192:195], v[32:35]
	v_mfma_f32_16x16x32_bf16 v[24:27], v[182:185], v[198:201], v[24:27]
	v_mfma_f32_16x16x32_bf16 v[16:19], v[182:185], v[204:207], v[16:19]
	s_waitcnt lgkmcnt(4)
	v_mfma_f32_16x16x32_bf16 v[100:103], v[156:159], v[224:227], v[100:103]
	v_add_u32_e32 v251, s11, v152
	v_add_u32_e32 v240, 0x2000, v251
	v_mfma_f32_16x16x32_bf16 v[92:95], v[156:159], v[228:231], v[92:95]
	v_readfirstlane_b32 s11, v251
	v_lshl_add_u64 v[174:175], v[144:145], 0, s[8:9]
	v_mfma_f32_16x16x32_bf16 v[84:87], v[156:159], v[232:235], v[84:87]
	ds_read_b128 v[186:189], v248 offset:32768
	s_mov_b32 m0, s11
	v_readfirstlane_b32 s11, v240
	v_mfma_f32_16x16x32_bf16 v[76:79], v[156:159], v[236:239], v[76:79]
	ds_read_b128 v[192:195], v248 offset:34816
	v_add_u32_e32 v240, 0x4000, v251
	global_load_lds_dwordx4 v[174:175], off
	v_mfma_f32_16x16x32_bf16 v[68:71], v[160:163], v[224:227], v[68:71]
	ds_read_b128 v[198:201], v248 offset:36864
	v_lshl_add_u64 v[174:175], v[134:135], 0, s[8:9]
	s_mov_b32 m0, s11
	v_mfma_f32_16x16x32_bf16 v[60:63], v[160:163], v[228:231], v[60:63]
	ds_read_b128 v[204:207], v248 offset:38912
	v_readfirstlane_b32 s11, v240
	v_add_u32_e32 v240, 0x6000, v251
	v_mfma_f32_16x16x32_bf16 v[52:55], v[160:163], v[232:235], v[52:55]
	global_load_lds_dwordx4 v[174:175], off
	v_lshl_add_u64 v[174:175], v[132:133], 0, s[8:9]
	v_mfma_f32_16x16x32_bf16 v[44:47], v[160:163], v[236:239], v[44:47]
	s_mov_b32 m0, s11
	v_readfirstlane_b32 s11, v240
	v_mfma_f32_16x16x32_bf16 v[36:39], v[178:181], v[224:227], v[36:39]
	global_load_lds_dwordx4 v[174:175], off
	v_lshl_add_u64 v[174:175], v[130:131], 0, s[8:9]
	v_mfma_f32_16x16x32_bf16 v[28:31], v[178:181], v[228:231], v[28:31]
	s_mov_b32 m0, s11
	v_add_u32_e32 v250, 0x8000, v251
	v_mfma_f32_16x16x32_bf16 v[20:23], v[178:181], v[232:235], v[20:23]
	global_load_lds_dwordx4 v[174:175], off
	v_lshl_add_u64 v[174:175], v[128:129], 0, s[8:9]
	v_mfma_f32_16x16x32_bf16 v[12:15], v[178:181], v[236:239], v[12:15]
	v_readfirstlane_b32 s11, v250
	v_add_u32_e32 v250, 0xa000, v251
	v_mfma_f32_16x16x32_bf16 v[8:11], v[182:185], v[224:227], v[8:11]
	v_lshl_add_u64 v[240:241], v[174:175], 0, s[66:67]
	s_mov_b32 m0, s11
	v_mfma_f32_16x16x32_bf16 v[4:7], v[182:185], v[228:231], v[4:7]
	s_mov_b64 s[12:13], 0x22080
	v_readfirstlane_b32 s11, v250
	v_mfma_f32_16x16x32_bf16 v[0:3], v[182:185], v[232:235], v[0:3]
	v_add_u32_e32 v250, 0xc000, v251
	global_load_lds_dwordx4 v[240:241], off
	v_mfma_f32_16x16x32_bf16 v[108:111], v[182:185], v[236:239], v[108:111]
	v_lshl_add_u64 v[240:241], v[174:175], 0, s[12:13]
	s_mov_b32 m0, s11
	s_waitcnt lgkmcnt(0)
	v_mfma_f32_16x16x32_bf16 v[124:127], v[208:211], v[186:189], v[124:127]
	ds_read_b128 v[224:227], v248 offset:40960
	s_mov_b64 s[12:13], 0x44080
	v_readfirstlane_b32 s11, v250
	v_mfma_f32_16x16x32_bf16 v[120:123], v[208:211], v[192:195], v[120:123]
	ds_read_b128 v[228:231], v248 offset:43008
	v_add_u32_e32 v251, 0xe000, v251
	global_load_lds_dwordx4 v[240:241], off
	v_mfma_f32_16x16x32_bf16 v[116:119], v[208:211], v[198:201], v[116:119]
	ds_read_b128 v[232:235], v248 offset:45056
	v_lshl_add_u64 v[240:241], v[174:175], 0, s[12:13]
	s_mov_b32 m0, s11
	v_mfma_f32_16x16x32_bf16 v[112:115], v[208:211], v[204:207], v[112:115]
	ds_read_b128 v[236:239], v248 offset:47104
	s_mov_b64 s[12:13], 0x66080
	v_readfirstlane_b32 s11, v251
	v_mfma_f32_16x16x32_bf16 v[104:107], v[212:215], v[186:189], v[104:107]
	global_load_lds_dwordx4 v[240:241], off
	v_lshl_add_u64 v[174:175], v[174:175], 0, s[12:13]
	v_mfma_f32_16x16x32_bf16 v[96:99], v[212:215], v[192:195], v[96:99]
	s_mov_b32 m0, s11
	global_load_lds_dwordx4 v[174:175], off
	v_mfma_f32_16x16x32_bf16 v[88:91], v[212:215], v[198:201], v[88:91]
	v_mfma_f32_16x16x32_bf16 v[80:83], v[212:215], v[204:207], v[80:83]
	v_mfma_f32_16x16x32_bf16 v[72:75], v[216:219], v[186:189], v[72:75]
	v_mfma_f32_16x16x32_bf16 v[64:67], v[216:219], v[192:195], v[64:67]
	v_mfma_f32_16x16x32_bf16 v[56:59], v[216:219], v[198:201], v[56:59]
	v_mfma_f32_16x16x32_bf16 v[48:51], v[216:219], v[204:207], v[48:51]
	v_mfma_f32_16x16x32_bf16 v[40:43], v[220:223], v[186:189], v[40:43]
	v_mfma_f32_16x16x32_bf16 v[32:35], v[220:223], v[192:195], v[32:35]
	v_mfma_f32_16x16x32_bf16 v[24:27], v[220:223], v[198:201], v[24:27]
	v_mfma_f32_16x16x32_bf16 v[16:19], v[220:223], v[204:207], v[16:19]
	s_waitcnt lgkmcnt(0)
	v_mfma_f32_16x16x32_bf16 v[100:103], v[208:211], v[224:227], v[100:103]
	v_mfma_f32_16x16x32_bf16 v[92:95], v[208:211], v[228:231], v[92:95]
	v_mfma_f32_16x16x32_bf16 v[84:87], v[208:211], v[232:235], v[84:87]
	v_mfma_f32_16x16x32_bf16 v[76:79], v[208:211], v[236:239], v[76:79]
	v_mfma_f32_16x16x32_bf16 v[68:71], v[212:215], v[224:227], v[68:71]
	v_mfma_f32_16x16x32_bf16 v[60:63], v[212:215], v[228:231], v[60:63]
	v_mfma_f32_16x16x32_bf16 v[52:55], v[212:215], v[232:235], v[52:55]
	v_mfma_f32_16x16x32_bf16 v[44:47], v[212:215], v[236:239], v[44:47]
	v_mfma_f32_16x16x32_bf16 v[36:39], v[216:219], v[224:227], v[36:39]
	v_mfma_f32_16x16x32_bf16 v[28:31], v[216:219], v[228:231], v[28:31]
	v_mfma_f32_16x16x32_bf16 v[20:23], v[216:219], v[232:235], v[20:23]
	v_mfma_f32_16x16x32_bf16 v[12:15], v[216:219], v[236:239], v[12:15]
	s_add_u32 s8, s8, 0x80
	s_addc_u32 s9, s9, 0
	s_cmpk_eq_i32 s8, 0x780
	s_mov_b32 s0, s1
	v_mfma_f32_16x16x32_bf16 v[8:11], v[220:223], v[224:227], v[8:11]
	v_mfma_f32_16x16x32_bf16 v[4:7], v[220:223], v[228:231], v[4:7]
	v_mfma_f32_16x16x32_bf16 v[0:3], v[220:223], v[232:235], v[0:3]
	v_mfma_f32_16x16x32_bf16 v[108:111], v[220:223], v[236:239], v[108:111]
	s_cbranch_scc0 .LBB0_212
	s_add_i32 s0, 0, 0x10000
	v_add_u32_e32 v144, s0, v154
	v_add_u32_e32 v162, s0, v153
	v_add_u32_e32 v145, v144, v151
	v_add_u32_e32 v151, v162, v151
	s_waitcnt vmcnt(0)
	s_barrier
	ds_read_b128 v[128:131], v145 offset:38912
	ds_read_b128 v[132:135], v145 offset:36864
	ds_read_b128 v[154:157], v145 offset:34816
	ds_read_b128 v[158:161], v145 offset:32768
	ds_read_b128 v[178:181], v151 offset:6144
	ds_read_b128 v[182:185], v151 offset:4096
	ds_read_b128 v[186:189], v151 offset:2048
	ds_read_b128 v[204:207], v151
	s_waitcnt lgkmcnt(0)
	v_mfma_f32_16x16x32_bf16 v[124:127], v[204:207], v[158:161], v[124:127]
	v_mfma_f32_16x16x32_bf16 v[120:123], v[204:207], v[154:157], v[120:123]
	v_mfma_f32_16x16x32_bf16 v[116:119], v[204:207], v[132:135], v[116:119]
	v_mfma_f32_16x16x32_bf16 v[112:115], v[204:207], v[128:131], v[112:115]
	v_mfma_f32_16x16x32_bf16 v[104:107], v[186:189], v[158:161], v[104:107]
	v_mfma_f32_16x16x32_bf16 v[72:75], v[182:185], v[158:161], v[72:75]
	v_mfma_f32_16x16x32_bf16 v[64:67], v[182:185], v[154:157], v[64:67]
	v_mfma_f32_16x16x32_bf16 v[56:59], v[182:185], v[132:135], v[56:59]
	v_mfma_f32_16x16x32_bf16 v[48:51], v[182:185], v[128:131], v[48:51]
	v_mfma_f32_16x16x32_bf16 v[208:211], v[186:189], v[154:157], v[96:99]
	v_mfma_f32_16x16x32_bf16 v[212:215], v[186:189], v[132:135], v[88:91]
	v_mfma_f32_16x16x32_bf16 v[216:219], v[186:189], v[128:131], v[80:83]
	v_mfma_f32_16x16x32_bf16 v[158:161], v[178:181], v[158:161], v[40:43]
	v_mfma_f32_16x16x32_bf16 v[152:155], v[178:181], v[154:157], v[32:35]
	v_mfma_f32_16x16x32_bf16 v[132:135], v[178:181], v[132:135], v[24:27]
	v_mfma_f32_16x16x32_bf16 v[128:131], v[178:181], v[128:131], v[16:19]
	s_nop 2
	ds_read_b128 v[16:19], v145 offset:40960
	ds_read_b128 v[24:27], v145 offset:43008
	ds_read_b128 v[32:35], v145 offset:45056
	ds_read_b128 v[40:43], v145 offset:47104
	s_waitcnt lgkmcnt(0)
	v_mfma_f32_16x16x32_bf16 v[100:103], v[204:207], v[16:19], v[100:103]
	v_mfma_f32_16x16x32_bf16 v[92:95], v[204:207], v[24:27], v[92:95]
	v_mfma_f32_16x16x32_bf16 v[220:223], v[204:207], v[32:35], v[84:87]
	v_mfma_f32_16x16x32_bf16 v[76:79], v[204:207], v[40:43], v[76:79]
	v_mfma_f32_16x16x32_bf16 v[68:71], v[186:189], v[16:19], v[68:71]
	v_mfma_f32_16x16x32_bf16 v[60:63], v[186:189], v[24:27], v[60:63]
	v_mfma_f32_16x16x32_bf16 v[204:207], v[186:189], v[32:35], v[52:55]
	v_mfma_f32_16x16x32_bf16 v[44:47], v[186:189], v[40:43], v[44:47]
	v_mfma_f32_16x16x32_bf16 v[186:189], v[182:185], v[16:19], v[36:39]
	v_mfma_f32_16x16x32_bf16 v[224:227], v[182:185], v[24:27], v[28:31]
	v_mfma_f32_16x16x32_bf16 v[228:231], v[182:185], v[32:35], v[20:23]
	v_mfma_f32_16x16x32_bf16 v[182:185], v[182:185], v[40:43], v[12:15]
	v_mfma_f32_16x16x32_bf16 v[232:235], v[178:181], v[16:19], v[8:11]
	v_mfma_f32_16x16x32_bf16 v[236:239], v[178:181], v[24:27], v[4:7]
	v_mfma_f32_16x16x32_bf16 v[240:243], v[178:181], v[32:35], v[0:3]
	v_mfma_f32_16x16x32_bf16 v[244:247], v[178:181], v[40:43], v[108:111]
	s_nop 1
	v_add_u32_e32 v0, v162, v150
	v_add_u32_e32 v144, v144, v150
	ds_read_b128 v[108:111], v0
	ds_read_b128 v[178:181], v0 offset:2048
	ds_read_b128 v[248:251], v0 offset:4096
	ds_read_b128 v[192:195], v0 offset:6144
	ds_read_b128 v[0:3], v144 offset:32768
	ds_read_b128 v[4:7], v144 offset:34816
	ds_read_b128 v[198:201], v144 offset:36864
	ds_read_b128 v[162:165], v144 offset:38912
	s_waitcnt lgkmcnt(0)
	v_mfma_f32_16x16x32_bf16 v[88:91], v[108:111], v[0:3], v[124:127]
	v_mfma_f32_16x16x32_bf16 v[96:99], v[108:111], v[4:7], v[120:123]
	v_mfma_f32_16x16x32_bf16 v[80:83], v[108:111], v[198:201], v[116:119]
	v_mfma_f32_16x16x32_bf16 v[84:87], v[108:111], v[162:165], v[112:115]
	v_mfma_f32_16x16x32_bf16 v[40:43], v[178:181], v[0:3], v[104:107]
	v_mfma_f32_16x16x32_bf16 v[52:55], v[178:181], v[4:7], v[208:211]
	v_mfma_f32_16x16x32_bf16 v[32:35], v[178:181], v[198:201], v[212:215]
	v_mfma_f32_16x16x32_bf16 v[36:39], v[178:181], v[162:165], v[216:219]
	v_mfma_f32_16x16x32_bf16 v[24:27], v[248:251], v[0:3], v[72:75]
	v_mfma_f32_16x16x32_bf16 v[28:31], v[248:251], v[4:7], v[64:67]
	v_mfma_f32_16x16x32_bf16 v[16:19], v[248:251], v[198:201], v[56:59]
	v_mfma_f32_16x16x32_bf16 v[20:23], v[248:251], v[162:165], v[48:51]
	v_mfma_f32_16x16x32_bf16 v[8:11], v[192:195], v[0:3], v[158:161]
	v_mfma_f32_16x16x32_bf16 v[12:15], v[192:195], v[4:7], v[152:155]
	v_mfma_f32_16x16x32_bf16 v[0:3], v[192:195], v[198:201], v[132:135]
	v_mfma_f32_16x16x32_bf16 v[4:7], v[192:195], v[162:165], v[128:131]
	ds_read_b128 v[48:51], v144 offset:40960
	ds_read_b128 v[64:67], v144 offset:43008
	s_nop 0
	ds_read_b128 v[128:131], v144 offset:45056
	ds_read_b128 v[132:135], v144 offset:47104
	s_waitcnt lgkmcnt(0)
	v_mfma_f32_16x16x32_bf16 v[104:107], v[178:181], v[48:51], v[68:71]
	v_cmp_ne_u32_e64 s[8:9], 0, v146
	v_cmp_eq_u32_e32 vcc, 0, v146
	s_waitcnt vmcnt(0)
	v_lshl_or_b32 v68, v148, 2, v149
	v_lshl_add_u32 v69, v147, 2, 0
	v_mfma_f32_16x16x32_bf16 v[120:123], v[108:111], v[48:51], v[100:103]
	s_barrier
	v_mfma_f32_16x16x32_bf16 v[124:127], v[108:111], v[64:67], v[92:95]
	v_mfma_f32_16x16x32_bf16 v[112:115], v[108:111], v[128:131], v[220:223]
	v_mfma_f32_16x16x32_bf16 v[116:119], v[108:111], v[132:135], v[76:79]
	v_mfma_f32_16x16x32_bf16 v[108:111], v[178:181], v[64:67], v[60:63]
	v_mfma_f32_16x16x32_bf16 v[92:95], v[178:181], v[128:131], v[204:207]
	v_mfma_f32_16x16x32_bf16 v[100:103], v[178:181], v[132:135], v[44:47]
	v_mfma_f32_16x16x32_bf16 v[56:59], v[248:251], v[48:51], v[186:189]
	v_mfma_f32_16x16x32_bf16 v[60:63], v[248:251], v[64:67], v[224:227]
	v_mfma_f32_16x16x32_bf16 v[44:47], v[248:251], v[128:131], v[228:231]
	v_mfma_f32_16x16x32_bf16 v[72:75], v[248:251], v[132:135], v[182:185]
	v_mfma_f32_16x16x32_bf16 v[48:51], v[192:195], v[48:51], v[232:235]
	s_nop 1
	v_lshl_add_u32 v182, v68, 9, v69
	v_add_u32_e32 v183, 0x400, v182
	v_add_u32_e32 v181, 0x2000, v182
	v_mfma_f32_16x16x32_bf16 v[64:67], v[192:195], v[64:67], v[236:239]
	v_add_u32_e32 v180, 0x2400, v182
	v_add_u32_e32 v179, 0x4000, v182
	v_add_u32_e32 v178, 0x4400, v182
	v_mfma_f32_16x16x32_bf16 v[68:71], v[192:195], v[128:131], v[240:243]
	v_add_u32_e32 v175, 0x6000, v182
	v_add_u32_e32 v174, 0x6400, v182
	v_mfma_f32_16x16x32_bf16 v[76:79], v[192:195], v[132:135], v[244:247]
	s_and_saveexec_b64 s[0:1], vcc
	s_cbranch_execz .LBB0_215
	ds_write2_b32 v182, v88, v96 offset1:16
	ds_write2_b32 v182, v89, v97 offset0:128 offset1:144
	ds_write2_b32 v183, v90, v98 offset1:16
	ds_write2_b32 v183, v91, v99 offset0:128 offset1:144
	ds_write2_b32 v182, v80, v84 offset0:32 offset1:48
	ds_write2_b32 v182, v81, v85 offset0:160 offset1:176
	ds_write2_b32 v183, v82, v86 offset0:32 offset1:48
	ds_write2_b32 v183, v83, v87 offset0:160 offset1:176
	ds_write2_b32 v182, v120, v124 offset0:64 offset1:80
	ds_write2_b32 v182, v121, v125 offset0:192 offset1:208
	ds_write2_b32 v183, v122, v126 offset0:64 offset1:80
	ds_write2_b32 v183, v123, v127 offset0:192 offset1:208
	ds_write2_b32 v182, v112, v116 offset0:96 offset1:112
	ds_write2_b32 v182, v113, v117 offset0:224 offset1:240
	ds_write2_b32 v183, v114, v118 offset0:96 offset1:112
	ds_write2_b32 v183, v115, v119 offset0:224 offset1:240
	ds_write2_b32 v181, v40, v52 offset1:16
	ds_write2_b32 v181, v41, v53 offset0:128 offset1:144
	ds_write2_b32 v180, v42, v54 offset1:16
	ds_write2_b32 v180, v43, v55 offset0:128 offset1:144
	ds_write2_b32 v181, v32, v36 offset0:32 offset1:48
	ds_write2_b32 v181, v33, v37 offset0:160 offset1:176
	ds_write2_b32 v180, v34, v38 offset0:32 offset1:48
	ds_write2_b32 v180, v35, v39 offset0:160 offset1:176
	ds_write2_b32 v181, v104, v108 offset0:64 offset1:80
	ds_write2_b32 v181, v105, v109 offset0:192 offset1:208
	ds_write2_b32 v180, v106, v110 offset0:64 offset1:80
	ds_write2_b32 v180, v107, v111 offset0:192 offset1:208
	ds_write2_b32 v181, v92, v100 offset0:96 offset1:112
	ds_write2_b32 v181, v93, v101 offset0:224 offset1:240
	ds_write2_b32 v180, v94, v102 offset0:96 offset1:112
	ds_write2_b32 v180, v95, v103 offset0:224 offset1:240
	ds_write2_b32 v179, v24, v28 offset1:16
	ds_write2_b32 v179, v25, v29 offset0:128 offset1:144
	ds_write2_b32 v178, v26, v30 offset1:16
	ds_write2_b32 v178, v27, v31 offset0:128 offset1:144
	ds_write2_b32 v179, v16, v20 offset0:32 offset1:48
	ds_write2_b32 v179, v17, v21 offset0:160 offset1:176
	ds_write2_b32 v178, v18, v22 offset0:32 offset1:48
	ds_write2_b32 v178, v19, v23 offset0:160 offset1:176
	ds_write2_b32 v179, v56, v60 offset0:64 offset1:80
	ds_write2_b32 v179, v57, v61 offset0:192 offset1:208
	ds_write2_b32 v178, v58, v62 offset0:64 offset1:80
	ds_write2_b32 v178, v59, v63 offset0:192 offset1:208
	ds_write2_b32 v179, v44, v72 offset0:96 offset1:112
	ds_write2_b32 v179, v45, v73 offset0:224 offset1:240
	ds_write2_b32 v178, v46, v74 offset0:96 offset1:112
	ds_write2_b32 v178, v47, v75 offset0:224 offset1:240
	ds_write2_b32 v175, v8, v12 offset1:16
	ds_write2_b32 v175, v9, v13 offset0:128 offset1:144
	ds_write2_b32 v174, v10, v14 offset1:16
	ds_write2_b32 v174, v11, v15 offset0:128 offset1:144
	ds_write2_b32 v175, v0, v4 offset0:32 offset1:48
	ds_write2_b32 v175, v1, v5 offset0:160 offset1:176
	ds_write2_b32 v174, v2, v6 offset0:32 offset1:48
	ds_write2_b32 v174, v3, v7 offset0:160 offset1:176
	ds_write2_b32 v175, v48, v64 offset0:64 offset1:80
	ds_write2_b32 v175, v49, v65 offset0:192 offset1:208
	ds_write2_b32 v174, v50, v66 offset0:64 offset1:80
	ds_write2_b32 v174, v51, v67 offset0:192 offset1:208
	ds_write2_b32 v175, v68, v76 offset0:96 offset1:112
	ds_write2_b32 v175, v69, v77 offset0:224 offset1:240
	ds_write2_b32 v174, v70, v78 offset0:96 offset1:112
	ds_write2_b32 v174, v71, v79 offset0:224 offset1:240

.LBB0_659:
	s_add_i32 s1, s0, 0x10000
	s_and_b32 s11, s1, 0x10000
	s_waitcnt vmcnt(0)
	s_barrier
	s_and_b32 s0, s0, 0x10000
	s_add_i32 s0, s0, 0
	v_add_u32_e32 v151, s0, v149
	v_add_u32_e32 v164, v151, v147
	ds_read_b128 v[152:155], v164
	ds_read_b128 v[156:159], v164 offset:2048
	ds_read_b128 v[160:163], v164 offset:4096
	ds_read_b128 v[164:167], v164 offset:6144
	v_add_u32_e32 v251, v151, v146
	v_add_u32_e32 v176, s0, v148
	v_add_u32_e32 v186, v176, v147
	ds_read_b128 v[168:171], v186 offset:32768
	ds_read_b128 v[172:175], v186 offset:34816
	ds_read_b128 v[178:181], v186 offset:36864
	ds_read_b128 v[182:185], v186 offset:38912
	v_add_u32_e32 v250, v176, v146
	s_waitcnt lgkmcnt(0)
	v_mfma_f32_16x16x32_bf16 v[124:127], v[152:155], v[168:171], v[124:127]
	ds_read_b128 v[212:215], v186 offset:40960
	v_mfma_f32_16x16x32_bf16 v[120:123], v[152:155], v[172:175], v[120:123]
	ds_read_b128 v[216:219], v186 offset:43008
	v_mfma_f32_16x16x32_bf16 v[116:119], v[152:155], v[178:181], v[116:119]
	ds_read_b128 v[220:223], v186 offset:45056
	v_mfma_f32_16x16x32_bf16 v[112:115], v[152:155], v[182:185], v[112:115]
	ds_read_b128 v[224:227], v186 offset:47104
	v_mfma_f32_16x16x32_bf16 v[104:107], v[156:159], v[168:171], v[104:107]
	ds_read_b128 v[192:195], v251
	v_mfma_f32_16x16x32_bf16 v[96:99], v[156:159], v[172:175], v[96:99]
	ds_read_b128 v[198:201], v251 offset:2048
	v_mfma_f32_16x16x32_bf16 v[88:91], v[156:159], v[178:181], v[88:91]
	ds_read_b128 v[204:207], v251 offset:4096
	v_mfma_f32_16x16x32_bf16 v[80:83], v[156:159], v[182:185], v[80:83]
	ds_read_b128 v[208:211], v251 offset:6144
	v_mfma_f32_16x16x32_bf16 v[72:75], v[160:163], v[168:171], v[72:75]
	v_mfma_f32_16x16x32_bf16 v[64:67], v[160:163], v[172:175], v[64:67]
	v_mfma_f32_16x16x32_bf16 v[56:59], v[160:163], v[178:181], v[56:59]
	v_mfma_f32_16x16x32_bf16 v[48:51], v[160:163], v[182:185], v[48:51]
	v_mfma_f32_16x16x32_bf16 v[40:43], v[164:167], v[168:171], v[40:43]
	v_mfma_f32_16x16x32_bf16 v[32:35], v[164:167], v[172:175], v[32:35]
	v_mfma_f32_16x16x32_bf16 v[24:27], v[164:167], v[178:181], v[24:27]
	v_mfma_f32_16x16x32_bf16 v[16:19], v[164:167], v[182:185], v[16:19]
	s_waitcnt lgkmcnt(4)
	v_mfma_f32_16x16x32_bf16 v[100:103], v[152:155], v[212:215], v[100:103]
	v_add_u32_e32 v254, s11, v150
	v_add_u32_e32 v228, 0x2000, v254
	v_mfma_f32_16x16x32_bf16 v[92:95], v[152:155], v[216:219], v[92:95]
	v_readfirstlane_b32 s11, v254
	v_lshl_add_u64 v[188:189], v[128:129], 0, s[2:3]
	v_mfma_f32_16x16x32_bf16 v[84:87], v[152:155], v[220:223], v[84:87]
	ds_read_b128 v[168:171], v250 offset:32768
	s_mov_b32 m0, s11
	v_readfirstlane_b32 s11, v228
	v_mfma_f32_16x16x32_bf16 v[76:79], v[152:155], v[224:227], v[76:79]
	ds_read_b128 v[172:175], v250 offset:34816
	v_add_u32_e32 v228, 0x4000, v254
	global_load_lds_dwordx4 v[188:189], off
	v_mfma_f32_16x16x32_bf16 v[68:71], v[156:159], v[212:215], v[68:71]
	ds_read_b128 v[178:181], v250 offset:36864
	v_lshl_add_u64 v[188:189], v[130:131], 0, s[2:3]
	s_mov_b32 m0, s11
	v_mfma_f32_16x16x32_bf16 v[60:63], v[156:159], v[216:219], v[60:63]
	ds_read_b128 v[182:185], v250 offset:38912
	v_readfirstlane_b32 s11, v228
	v_add_u32_e32 v228, 0x6000, v254
	v_mfma_f32_16x16x32_bf16 v[52:55], v[156:159], v[220:223], v[52:55]
	global_load_lds_dwordx4 v[188:189], off
	v_lshl_add_u64 v[188:189], v[132:133], 0, s[2:3]
	v_mfma_f32_16x16x32_bf16 v[44:47], v[156:159], v[224:227], v[44:47]
	s_mov_b32 m0, s11
	v_readfirstlane_b32 s11, v228
	v_mfma_f32_16x16x32_bf16 v[36:39], v[160:163], v[212:215], v[36:39]
	global_load_lds_dwordx4 v[188:189], off
	v_lshl_add_u64 v[188:189], v[134:135], 0, s[2:3]
	v_mfma_f32_16x16x32_bf16 v[28:31], v[160:163], v[216:219], v[28:31]
	s_mov_b32 m0, s11
	v_add_u32_e32 v253, 0x8000, v254
	v_mfma_f32_16x16x32_bf16 v[20:23], v[160:163], v[220:223], v[20:23]
	global_load_lds_dwordx4 v[188:189], off
	v_lshl_add_u64 v[188:189], v[136:137], 0, s[2:3]
	v_mfma_f32_16x16x32_bf16 v[12:15], v[160:163], v[224:227], v[12:15]
	s_mov_b64 s[18:19], 0x550080
	v_readfirstlane_b32 s11, v253
	v_mfma_f32_16x16x32_bf16 v[8:11], v[164:167], v[212:215], v[8:11]
	v_add_u32_e32 v253, 0xa000, v254
	v_lshl_add_u64 v[228:229], v[188:189], 0, s[18:19]
	v_mfma_f32_16x16x32_bf16 v[4:7], v[164:167], v[216:219], v[4:7]
	s_mov_b32 m0, s11
	s_mov_b64 s[18:19], 0x572080
	v_mfma_f32_16x16x32_bf16 v[0:3], v[164:167], v[220:223], v[0:3]
	v_readfirstlane_b32 s11, v253
	v_add_u32_e32 v253, 0xc000, v254
	v_mfma_f32_16x16x32_bf16 v[108:111], v[164:167], v[224:227], v[108:111]
	global_load_lds_dwordx4 v[228:229], off
	v_lshl_add_u64 v[228:229], v[188:189], 0, s[18:19]
	s_waitcnt lgkmcnt(0)
	v_mfma_f32_16x16x32_bf16 v[124:127], v[192:195], v[168:171], v[124:127]
	ds_read_b128 v[212:215], v250 offset:40960
	s_mov_b32 m0, s11
	s_mov_b64 s[18:19], 0x594080
	v_mfma_f32_16x16x32_bf16 v[120:123], v[192:195], v[172:175], v[120:123]
	ds_read_b128 v[216:219], v250 offset:43008
	v_readfirstlane_b32 s11, v253
	v_add_u32_e32 v254, 0xe000, v254
	v_mfma_f32_16x16x32_bf16 v[116:119], v[192:195], v[178:181], v[116:119]
	ds_read_b128 v[220:223], v250 offset:45056
	global_load_lds_dwordx4 v[228:229], off
	v_lshl_add_u64 v[228:229], v[188:189], 0, s[18:19]
	v_mfma_f32_16x16x32_bf16 v[112:115], v[192:195], v[182:185], v[112:115]
	ds_read_b128 v[224:227], v250 offset:47104
	s_mov_b32 m0, s11
	s_mov_b64 s[18:19], 0x5b6080
	v_mfma_f32_16x16x32_bf16 v[104:107], v[198:201], v[168:171], v[104:107]
	v_readfirstlane_b32 s11, v254
	global_load_lds_dwordx4 v[228:229], off
	v_mfma_f32_16x16x32_bf16 v[96:99], v[198:201], v[172:175], v[96:99]
	v_lshl_add_u64 v[188:189], v[188:189], 0, s[18:19]
	s_mov_b32 m0, s11
	v_mfma_f32_16x16x32_bf16 v[88:91], v[198:201], v[178:181], v[88:91]
	global_load_lds_dwordx4 v[188:189], off
	v_mfma_f32_16x16x32_bf16 v[80:83], v[198:201], v[182:185], v[80:83]
	v_mfma_f32_16x16x32_bf16 v[72:75], v[204:207], v[168:171], v[72:75]
	v_mfma_f32_16x16x32_bf16 v[64:67], v[204:207], v[172:175], v[64:67]
	v_mfma_f32_16x16x32_bf16 v[56:59], v[204:207], v[178:181], v[56:59]
	v_mfma_f32_16x16x32_bf16 v[48:51], v[204:207], v[182:185], v[48:51]
	v_mfma_f32_16x16x32_bf16 v[40:43], v[208:211], v[168:171], v[40:43]
	v_mfma_f32_16x16x32_bf16 v[32:35], v[208:211], v[172:175], v[32:35]
	v_mfma_f32_16x16x32_bf16 v[24:27], v[208:211], v[178:181], v[24:27]
	v_mfma_f32_16x16x32_bf16 v[16:19], v[208:211], v[182:185], v[16:19]
	s_waitcnt lgkmcnt(0)
	v_mfma_f32_16x16x32_bf16 v[100:103], v[192:195], v[212:215], v[100:103]
	v_mfma_f32_16x16x32_bf16 v[92:95], v[192:195], v[216:219], v[92:95]
	v_mfma_f32_16x16x32_bf16 v[84:87], v[192:195], v[220:223], v[84:87]
	v_mfma_f32_16x16x32_bf16 v[76:79], v[192:195], v[224:227], v[76:79]
	v_mfma_f32_16x16x32_bf16 v[68:71], v[198:201], v[212:215], v[68:71]
	v_mfma_f32_16x16x32_bf16 v[60:63], v[198:201], v[216:219], v[60:63]
	v_mfma_f32_16x16x32_bf16 v[52:55], v[198:201], v[220:223], v[52:55]
	v_mfma_f32_16x16x32_bf16 v[44:47], v[198:201], v[224:227], v[44:47]
	v_mfma_f32_16x16x32_bf16 v[36:39], v[204:207], v[212:215], v[36:39]
	v_mfma_f32_16x16x32_bf16 v[28:31], v[204:207], v[216:219], v[28:31]
	v_mfma_f32_16x16x32_bf16 v[20:23], v[204:207], v[220:223], v[20:23]
	v_mfma_f32_16x16x32_bf16 v[12:15], v[204:207], v[224:227], v[12:15]
	s_add_u32 s2, s2, 0x80
	s_addc_u32 s3, s3, 0
	s_cmpk_eq_i32 s2, 0x780
	s_mov_b32 s0, s1
	v_mfma_f32_16x16x32_bf16 v[8:11], v[208:211], v[212:215], v[8:11]
	v_mfma_f32_16x16x32_bf16 v[4:7], v[208:211], v[216:219], v[4:7]
	v_mfma_f32_16x16x32_bf16 v[0:3], v[208:211], v[220:223], v[0:3]
	v_mfma_f32_16x16x32_bf16 v[108:111], v[208:211], v[224:227], v[108:111]
	s_cbranch_scc0 .LBB0_659
	s_add_i32 s0, 0, 0x10000
	v_add_u32_e32 v136, s0, v149
	v_add_u32_e32 v137, v136, v147
	s_waitcnt vmcnt(0)
	s_barrier
	ds_read_b128 v[128:131], v137
	ds_read_b128 v[132:135], v137 offset:2048
	ds_read_b128 v[150:153], v137 offset:4096
	ds_read_b128 v[154:157], v137 offset:6144
	v_add_u32_e32 v137, s0, v148
	v_add_u32_e32 v147, v137, v147
	ds_read_b128 v[158:161], v147 offset:32768
	ds_read_b128 v[162:165], v147 offset:34816
	ds_read_b128 v[166:169], v147 offset:36864
	ds_read_b128 v[170:173], v147 offset:38912
	s_waitcnt lgkmcnt(0)
	v_mfma_f32_16x16x32_bf16 v[124:127], v[128:131], v[158:161], v[124:127]
	v_mfma_f32_16x16x32_bf16 v[120:123], v[128:131], v[162:165], v[120:123]
	v_mfma_f32_16x16x32_bf16 v[116:119], v[128:131], v[166:169], v[116:119]
	v_mfma_f32_16x16x32_bf16 v[112:115], v[128:131], v[170:173], v[112:115]
	v_mfma_f32_16x16x32_bf16 v[104:107], v[132:135], v[158:161], v[104:107]
	v_mfma_f32_16x16x32_bf16 v[72:75], v[150:153], v[158:161], v[72:75]
	v_mfma_f32_16x16x32_bf16 v[64:67], v[150:153], v[162:165], v[64:67]
	v_mfma_f32_16x16x32_bf16 v[56:59], v[150:153], v[166:169], v[56:59]
	v_mfma_f32_16x16x32_bf16 v[48:51], v[150:153], v[170:173], v[48:51]
	v_mfma_f32_16x16x32_bf16 v[178:181], v[132:135], v[162:165], v[96:99]
	v_mfma_f32_16x16x32_bf16 v[182:185], v[132:135], v[166:169], v[88:91]
	v_mfma_f32_16x16x32_bf16 v[186:189], v[132:135], v[170:173], v[80:83]
	v_mfma_f32_16x16x32_bf16 v[158:161], v[154:157], v[158:161], v[40:43]
	v_mfma_f32_16x16x32_bf16 v[162:165], v[154:157], v[162:165], v[32:35]
	v_mfma_f32_16x16x32_bf16 v[166:169], v[154:157], v[166:169], v[24:27]
	v_mfma_f32_16x16x32_bf16 v[170:173], v[154:157], v[170:173], v[16:19]
	s_nop 2
	ds_read_b128 v[16:19], v147 offset:40960
	ds_read_b128 v[24:27], v147 offset:43008
	ds_read_b128 v[32:35], v147 offset:45056
	ds_read_b128 v[40:43], v147 offset:47104
	s_waitcnt lgkmcnt(0)
	v_mfma_f32_16x16x32_bf16 v[100:103], v[128:131], v[16:19], v[100:103]
	v_mfma_f32_16x16x32_bf16 v[92:95], v[128:131], v[24:27], v[92:95]
	v_mfma_f32_16x16x32_bf16 v[192:195], v[128:131], v[32:35], v[84:87]
	v_mfma_f32_16x16x32_bf16 v[76:79], v[128:131], v[40:43], v[76:79]
	v_mfma_f32_16x16x32_bf16 v[68:71], v[132:135], v[16:19], v[68:71]
	v_mfma_f32_16x16x32_bf16 v[60:63], v[132:135], v[24:27], v[60:63]
	v_mfma_f32_16x16x32_bf16 v[128:131], v[132:135], v[32:35], v[52:55]
	v_mfma_f32_16x16x32_bf16 v[44:47], v[132:135], v[40:43], v[44:47]
	v_mfma_f32_16x16x32_bf16 v[132:135], v[150:153], v[16:19], v[36:39]
	v_mfma_f32_16x16x32_bf16 v[198:201], v[150:153], v[24:27], v[28:31]
	v_mfma_f32_16x16x32_bf16 v[204:207], v[150:153], v[32:35], v[20:23]
	v_mfma_f32_16x16x32_bf16 v[148:151], v[150:153], v[40:43], v[12:15]
	v_mfma_f32_16x16x32_bf16 v[208:211], v[154:157], v[16:19], v[8:11]
	v_mfma_f32_16x16x32_bf16 v[212:215], v[154:157], v[24:27], v[4:7]
	v_mfma_f32_16x16x32_bf16 v[216:219], v[154:157], v[32:35], v[0:3]
	v_mfma_f32_16x16x32_bf16 v[154:157], v[154:157], v[40:43], v[108:111]
	s_nop 1
	v_add_u32_e32 v0, v136, v146
	v_add_u32_e32 v136, v137, v146
	ds_read_b128 v[108:111], v0
	ds_read_b128 v[220:223], v0 offset:2048
	ds_read_b128 v[224:227], v0 offset:4096
	ds_read_b128 v[228:231], v0 offset:6144
	ds_read_b128 v[0:3], v136 offset:32768
	ds_read_b128 v[4:7], v136 offset:34816
	ds_read_b128 v[232:235], v136 offset:36864
	ds_read_b128 v[236:239], v136 offset:38912
	s_waitcnt lgkmcnt(0)
	v_mfma_f32_16x16x32_bf16 v[88:91], v[108:111], v[0:3], v[124:127]
	v_mfma_f32_16x16x32_bf16 v[96:99], v[108:111], v[4:7], v[120:123]
	v_mfma_f32_16x16x32_bf16 v[80:83], v[108:111], v[232:235], v[116:119]
	v_mfma_f32_16x16x32_bf16 v[84:87], v[108:111], v[236:239], v[112:115]
	v_mfma_f32_16x16x32_bf16 v[40:43], v[220:223], v[0:3], v[104:107]
	v_mfma_f32_16x16x32_bf16 v[52:55], v[220:223], v[4:7], v[178:181]
	v_mfma_f32_16x16x32_bf16 v[32:35], v[220:223], v[232:235], v[182:185]
	v_mfma_f32_16x16x32_bf16 v[36:39], v[220:223], v[236:239], v[186:189]
	v_mfma_f32_16x16x32_bf16 v[24:27], v[224:227], v[0:3], v[72:75]
	v_mfma_f32_16x16x32_bf16 v[28:31], v[224:227], v[4:7], v[64:67]
	v_mfma_f32_16x16x32_bf16 v[16:19], v[224:227], v[232:235], v[56:59]
	v_mfma_f32_16x16x32_bf16 v[20:23], v[224:227], v[236:239], v[48:51]
	v_mfma_f32_16x16x32_bf16 v[8:11], v[228:231], v[0:3], v[158:161]
	v_mfma_f32_16x16x32_bf16 v[12:15], v[228:231], v[4:7], v[162:165]
	v_mfma_f32_16x16x32_bf16 v[0:3], v[228:231], v[232:235], v[166:169]
	v_mfma_f32_16x16x32_bf16 v[4:7], v[228:231], v[236:239], v[170:173]
	ds_read_b128 v[48:51], v136 offset:40960
	ds_read_b128 v[64:67], v136 offset:43008
	ds_read_b128 v[158:161], v136 offset:45056
	ds_read_b128 v[162:165], v136 offset:47104
	s_waitcnt lgkmcnt(0)
	v_mfma_f32_16x16x32_bf16 v[104:107], v[220:223], v[48:51], v[68:71]
	v_cmp_ne_u32_e32 vcc, 0, v138
	v_cmp_eq_u32_e64 s[2:3], 0, v138
	s_waitcnt vmcnt(0)
	v_lshl_or_b32 v68, v140, 2, v141
	v_lshl_add_u32 v69, v139, 2, 0
	v_mfma_f32_16x16x32_bf16 v[120:123], v[108:111], v[48:51], v[100:103]
	v_lshl_add_u32 v152, v68, 9, v69
	v_add_u32_e32 v153, 0x400, v152
	v_add_u32_e32 v147, 0x6000, v152
	v_mfma_f32_16x16x32_bf16 v[124:127], v[108:111], v[64:67], v[92:95]
	v_add_u32_e32 v146, 0x6400, v152
	s_barrier
	v_mfma_f32_16x16x32_bf16 v[112:115], v[108:111], v[158:161], v[192:195]
	v_mfma_f32_16x16x32_bf16 v[116:119], v[108:111], v[162:165], v[76:79]
	v_mfma_f32_16x16x32_bf16 v[108:111], v[220:223], v[64:67], v[60:63]
	v_mfma_f32_16x16x32_bf16 v[92:95], v[220:223], v[158:161], v[128:131]
	v_mfma_f32_16x16x32_bf16 v[100:103], v[220:223], v[162:165], v[44:47]
	v_mfma_f32_16x16x32_bf16 v[56:59], v[224:227], v[48:51], v[132:135]
	v_mfma_f32_16x16x32_bf16 v[60:63], v[224:227], v[64:67], v[198:201]
	v_mfma_f32_16x16x32_bf16 v[44:47], v[224:227], v[158:161], v[204:207]
	v_mfma_f32_16x16x32_bf16 v[72:75], v[224:227], v[162:165], v[148:151]
	v_mfma_f32_16x16x32_bf16 v[48:51], v[228:231], v[48:51], v[208:211]
	s_nop 1
	v_add_u32_e32 v151, 0x2000, v152
	v_add_u32_e32 v150, 0x2400, v152
	v_add_u32_e32 v149, 0x4000, v152
	v_mfma_f32_16x16x32_bf16 v[64:67], v[228:231], v[64:67], v[212:215]
	v_add_u32_e32 v148, 0x4400, v152
	v_mfma_f32_16x16x32_bf16 v[68:71], v[228:231], v[158:161], v[216:219]
	v_mfma_f32_16x16x32_bf16 v[76:79], v[228:231], v[162:165], v[154:157]
	s_and_saveexec_b64 s[0:1], s[2:3]
	s_cbranch_execz .LBB0_662
	ds_write2_b32 v152, v88, v96 offset1:16
	ds_write2_b32 v152, v89, v97 offset0:128 offset1:144
	ds_write2_b32 v153, v90, v98 offset1:16
	ds_write2_b32 v153, v91, v99 offset0:128 offset1:144
	ds_write2_b32 v152, v80, v84 offset0:32 offset1:48
	ds_write2_b32 v152, v81, v85 offset0:160 offset1:176
	ds_write2_b32 v153, v82, v86 offset0:32 offset1:48
	ds_write2_b32 v153, v83, v87 offset0:160 offset1:176
	ds_write2_b32 v152, v120, v124 offset0:64 offset1:80
	ds_write2_b32 v152, v121, v125 offset0:192 offset1:208
	ds_write2_b32 v153, v122, v126 offset0:64 offset1:80
	ds_write2_b32 v153, v123, v127 offset0:192 offset1:208
	ds_write2_b32 v152, v112, v116 offset0:96 offset1:112
	ds_write2_b32 v152, v113, v117 offset0:224 offset1:240
	ds_write2_b32 v153, v114, v118 offset0:96 offset1:112
	ds_write2_b32 v153, v115, v119 offset0:224 offset1:240
	ds_write2_b32 v151, v40, v52 offset1:16
	ds_write2_b32 v151, v41, v53 offset0:128 offset1:144
	ds_write2_b32 v150, v42, v54 offset1:16
	ds_write2_b32 v150, v43, v55 offset0:128 offset1:144
	ds_write2_b32 v151, v32, v36 offset0:32 offset1:48
	ds_write2_b32 v151, v33, v37 offset0:160 offset1:176
	ds_write2_b32 v150, v34, v38 offset0:32 offset1:48
	ds_write2_b32 v150, v35, v39 offset0:160 offset1:176
	ds_write2_b32 v151, v104, v108 offset0:64 offset1:80
	ds_write2_b32 v151, v105, v109 offset0:192 offset1:208
	ds_write2_b32 v150, v106, v110 offset0:64 offset1:80
	ds_write2_b32 v150, v107, v111 offset0:192 offset1:208
	ds_write2_b32 v151, v92, v100 offset0:96 offset1:112
	ds_write2_b32 v151, v93, v101 offset0:224 offset1:240
	ds_write2_b32 v150, v94, v102 offset0:96 offset1:112
	ds_write2_b32 v150, v95, v103 offset0:224 offset1:240
	ds_write2_b32 v149, v24, v28 offset1:16
	ds_write2_b32 v149, v25, v29 offset0:128 offset1:144
	ds_write2_b32 v148, v26, v30 offset1:16
	ds_write2_b32 v148, v27, v31 offset0:128 offset1:144
	ds_write2_b32 v149, v16, v20 offset0:32 offset1:48
	ds_write2_b32 v149, v17, v21 offset0:160 offset1:176
	ds_write2_b32 v148, v18, v22 offset0:32 offset1:48
	ds_write2_b32 v148, v19, v23 offset0:160 offset1:176
	ds_write2_b32 v149, v56, v60 offset0:64 offset1:80
	ds_write2_b32 v149, v57, v61 offset0:192 offset1:208
	ds_write2_b32 v148, v58, v62 offset0:64 offset1:80
	ds_write2_b32 v148, v59, v63 offset0:192 offset1:208
	ds_write2_b32 v149, v44, v72 offset0:96 offset1:112
	ds_write2_b32 v149, v45, v73 offset0:224 offset1:240
	ds_write2_b32 v148, v46, v74 offset0:96 offset1:112
	ds_write2_b32 v148, v47, v75 offset0:224 offset1:240
	ds_write2_b32 v147, v8, v12 offset1:16
	ds_write2_b32 v147, v9, v13 offset0:128 offset1:144
	ds_write2_b32 v146, v10, v14 offset1:16
	ds_write2_b32 v146, v11, v15 offset0:128 offset1:144
	ds_write2_b32 v147, v0, v4 offset0:32 offset1:48
	ds_write2_b32 v147, v1, v5 offset0:160 offset1:176
	ds_write2_b32 v146, v2, v6 offset0:32 offset1:48
	ds_write2_b32 v146, v3, v7 offset0:160 offset1:176
	ds_write2_b32 v147, v48, v64 offset0:64 offset1:80
	ds_write2_b32 v147, v49, v65 offset0:192 offset1:208
	ds_write2_b32 v146, v50, v66 offset0:64 offset1:80
	ds_write2_b32 v146, v51, v67 offset0:192 offset1:208
	ds_write2_b32 v147, v68, v76 offset0:96 offset1:112
	ds_write2_b32 v147, v69, v77 offset0:224 offset1:240
	ds_write2_b32 v146, v70, v78 offset0:96 offset1:112
	ds_write2_b32 v146, v71, v79 offset0:224 offset1:240

.LBB0_1074:
	s_add_i32 s5, s4, 0x10000
	s_and_b32 s40, s5, 0x10000
	s_waitcnt vmcnt(0)
	s_barrier
	s_and_b32 s4, s4, 0x10000
	s_add_i32 s4, s4, 0
	v_add_u32_e32 v147, s4, v144
	v_add_u32_e32 v160, v147, v143
	ds_read_b128 v[148:151], v160
	ds_read_b128 v[152:155], v160 offset:2048
	ds_read_b128 v[156:159], v160 offset:4096
	ds_read_b128 v[170:173], v160 offset:6144
	v_add_u32_e32 v251, v147, v142
	v_add_u32_e32 v160, s4, v145
	v_add_u32_e32 v161, v160, v143
	ds_read_b128 v[178:181], v161 offset:32768
	ds_read_b128 v[182:185], v161 offset:34816
	ds_read_b128 v[186:189], v161 offset:36864
	ds_read_b128 v[192:195], v161 offset:38912
	v_add_u32_e32 v250, v160, v142
	s_waitcnt lgkmcnt(0)
	v_mfma_f32_16x16x32_bf16 v[124:127], v[148:151], v[178:181], v[124:127]
	ds_read_b128 v[216:219], v161 offset:40960
	v_mfma_f32_16x16x32_bf16 v[120:123], v[148:151], v[182:185], v[120:123]
	ds_read_b128 v[220:223], v161 offset:43008
	v_mfma_f32_16x16x32_bf16 v[116:119], v[148:151], v[186:189], v[116:119]
	ds_read_b128 v[224:227], v161 offset:45056
	v_mfma_f32_16x16x32_bf16 v[112:115], v[148:151], v[192:195], v[112:115]
	ds_read_b128 v[228:231], v161 offset:47104
	v_mfma_f32_16x16x32_bf16 v[104:107], v[152:155], v[178:181], v[104:107]
	ds_read_b128 v[198:201], v251
	v_mfma_f32_16x16x32_bf16 v[96:99], v[152:155], v[182:185], v[96:99]
	ds_read_b128 v[204:207], v251 offset:2048
	v_mfma_f32_16x16x32_bf16 v[88:91], v[152:155], v[186:189], v[88:91]
	ds_read_b128 v[208:211], v251 offset:4096
	v_mfma_f32_16x16x32_bf16 v[80:83], v[152:155], v[192:195], v[80:83]
	ds_read_b128 v[212:215], v251 offset:6144
	v_mfma_f32_16x16x32_bf16 v[72:75], v[156:159], v[178:181], v[72:75]
	v_mfma_f32_16x16x32_bf16 v[64:67], v[156:159], v[182:185], v[64:67]
	v_mfma_f32_16x16x32_bf16 v[56:59], v[156:159], v[186:189], v[56:59]
	v_mfma_f32_16x16x32_bf16 v[48:51], v[156:159], v[192:195], v[48:51]
	v_mfma_f32_16x16x32_bf16 v[40:43], v[170:173], v[178:181], v[40:43]
	v_mfma_f32_16x16x32_bf16 v[32:35], v[170:173], v[182:185], v[32:35]
	v_mfma_f32_16x16x32_bf16 v[24:27], v[170:173], v[186:189], v[24:27]
	v_mfma_f32_16x16x32_bf16 v[16:19], v[170:173], v[192:195], v[16:19]
	s_waitcnt lgkmcnt(4)
	v_mfma_f32_16x16x32_bf16 v[100:103], v[148:151], v[216:219], v[100:103]
	v_add_u32_e32 v254, s40, v146
	v_add_u32_e32 v232, 0x2000, v254
	v_mfma_f32_16x16x32_bf16 v[92:95], v[148:151], v[220:223], v[92:95]
	v_readfirstlane_b32 s40, v254
	v_lshl_add_u64 v[174:175], v[136:137], 0, s[2:3]
	v_mfma_f32_16x16x32_bf16 v[84:87], v[148:151], v[224:227], v[84:87]
	ds_read_b128 v[178:181], v250 offset:32768
	s_mov_b32 m0, s40
	v_readfirstlane_b32 s40, v232
	v_mfma_f32_16x16x32_bf16 v[76:79], v[148:151], v[228:231], v[76:79]
	ds_read_b128 v[182:185], v250 offset:34816
	v_add_u32_e32 v232, 0x4000, v254
	global_load_lds_dwordx4 v[174:175], off
	v_mfma_f32_16x16x32_bf16 v[68:71], v[152:155], v[216:219], v[68:71]
	ds_read_b128 v[186:189], v250 offset:36864
	v_lshl_add_u64 v[174:175], v[134:135], 0, s[2:3]
	s_mov_b32 m0, s40
	v_mfma_f32_16x16x32_bf16 v[60:63], v[152:155], v[220:223], v[60:63]
	ds_read_b128 v[192:195], v250 offset:38912
	v_readfirstlane_b32 s40, v232
	v_add_u32_e32 v232, 0x6000, v254
	v_mfma_f32_16x16x32_bf16 v[52:55], v[152:155], v[224:227], v[52:55]
	global_load_lds_dwordx4 v[174:175], off
	v_lshl_add_u64 v[174:175], v[132:133], 0, s[2:3]
	v_mfma_f32_16x16x32_bf16 v[44:47], v[152:155], v[228:231], v[44:47]
	s_mov_b32 m0, s40
	v_readfirstlane_b32 s40, v232
	v_mfma_f32_16x16x32_bf16 v[36:39], v[156:159], v[216:219], v[36:39]
	global_load_lds_dwordx4 v[174:175], off
	v_lshl_add_u64 v[174:175], v[130:131], 0, s[2:3]
	v_mfma_f32_16x16x32_bf16 v[28:31], v[156:159], v[220:223], v[28:31]
	s_mov_b32 m0, s40
	s_mov_b64 s[40:41], 0x770080
	v_mfma_f32_16x16x32_bf16 v[20:23], v[156:159], v[224:227], v[20:23]
	global_load_lds_dwordx4 v[174:175], off
	v_lshl_add_u64 v[174:175], v[128:129], 0, s[2:3]
	v_mfma_f32_16x16x32_bf16 v[12:15], v[156:159], v[228:231], v[12:15]
	v_add_u32_e32 v253, 0x8000, v254
	v_lshl_add_u64 v[232:233], v[174:175], 0, s[40:41]
	v_mfma_f32_16x16x32_bf16 v[8:11], v[170:173], v[216:219], v[8:11]
	v_readfirstlane_b32 s40, v253
	s_mov_b32 m0, s40
	v_mfma_f32_16x16x32_bf16 v[4:7], v[170:173], v[220:223], v[4:7]
	s_mov_b64 s[40:41], 0x792080
	v_add_u32_e32 v253, 0xa000, v254
	v_mfma_f32_16x16x32_bf16 v[0:3], v[170:173], v[224:227], v[0:3]
	global_load_lds_dwordx4 v[232:233], off
	v_lshl_add_u64 v[232:233], v[174:175], 0, s[40:41]
	v_mfma_f32_16x16x32_bf16 v[108:111], v[170:173], v[228:231], v[108:111]
	v_readfirstlane_b32 s40, v253
	s_mov_b32 m0, s40
	s_waitcnt lgkmcnt(0)
	v_mfma_f32_16x16x32_bf16 v[124:127], v[198:201], v[178:181], v[124:127]
	ds_read_b128 v[216:219], v250 offset:40960
	s_mov_b64 s[40:41], 0x7b4080
	v_add_u32_e32 v253, 0xc000, v254
	v_mfma_f32_16x16x32_bf16 v[120:123], v[198:201], v[182:185], v[120:123]
	ds_read_b128 v[220:223], v250 offset:43008
	global_load_lds_dwordx4 v[232:233], off
	v_lshl_add_u64 v[232:233], v[174:175], 0, s[40:41]
	v_mfma_f32_16x16x32_bf16 v[116:119], v[198:201], v[186:189], v[116:119]
	ds_read_b128 v[224:227], v250 offset:45056
	v_readfirstlane_b32 s40, v253
	s_mov_b32 m0, s40
	v_mfma_f32_16x16x32_bf16 v[112:115], v[198:201], v[192:195], v[112:115]
	ds_read_b128 v[228:231], v250 offset:47104
	s_mov_b64 s[40:41], 0x7d6080
	v_add_u32_e32 v254, 0xe000, v254
	v_mfma_f32_16x16x32_bf16 v[104:107], v[204:207], v[178:181], v[104:107]
	v_lshl_add_u64 v[174:175], v[174:175], 0, s[40:41]
	v_readfirstlane_b32 s40, v254
	v_mfma_f32_16x16x32_bf16 v[96:99], v[204:207], v[182:185], v[96:99]
	global_load_lds_dwordx4 v[232:233], off
	s_mov_b32 m0, s40
	v_mfma_f32_16x16x32_bf16 v[88:91], v[204:207], v[186:189], v[88:91]
	global_load_lds_dwordx4 v[174:175], off
	v_mfma_f32_16x16x32_bf16 v[80:83], v[204:207], v[192:195], v[80:83]
	v_mfma_f32_16x16x32_bf16 v[72:75], v[208:211], v[178:181], v[72:75]
	v_mfma_f32_16x16x32_bf16 v[64:67], v[208:211], v[182:185], v[64:67]
	v_mfma_f32_16x16x32_bf16 v[56:59], v[208:211], v[186:189], v[56:59]
	v_mfma_f32_16x16x32_bf16 v[48:51], v[208:211], v[192:195], v[48:51]
	v_mfma_f32_16x16x32_bf16 v[40:43], v[212:215], v[178:181], v[40:43]
	v_mfma_f32_16x16x32_bf16 v[32:35], v[212:215], v[182:185], v[32:35]
	v_mfma_f32_16x16x32_bf16 v[24:27], v[212:215], v[186:189], v[24:27]
	v_mfma_f32_16x16x32_bf16 v[16:19], v[212:215], v[192:195], v[16:19]
	s_waitcnt lgkmcnt(0)
	v_mfma_f32_16x16x32_bf16 v[100:103], v[198:201], v[216:219], v[100:103]
	v_mfma_f32_16x16x32_bf16 v[92:95], v[198:201], v[220:223], v[92:95]
	v_mfma_f32_16x16x32_bf16 v[84:87], v[198:201], v[224:227], v[84:87]
	v_mfma_f32_16x16x32_bf16 v[76:79], v[198:201], v[228:231], v[76:79]
	v_mfma_f32_16x16x32_bf16 v[68:71], v[204:207], v[216:219], v[68:71]
	v_mfma_f32_16x16x32_bf16 v[60:63], v[204:207], v[220:223], v[60:63]
	v_mfma_f32_16x16x32_bf16 v[52:55], v[204:207], v[224:227], v[52:55]
	v_mfma_f32_16x16x32_bf16 v[44:47], v[204:207], v[228:231], v[44:47]
	v_mfma_f32_16x16x32_bf16 v[36:39], v[208:211], v[216:219], v[36:39]
	v_mfma_f32_16x16x32_bf16 v[28:31], v[208:211], v[220:223], v[28:31]
	v_mfma_f32_16x16x32_bf16 v[20:23], v[208:211], v[224:227], v[20:23]
	v_mfma_f32_16x16x32_bf16 v[12:15], v[208:211], v[228:231], v[12:15]
	s_add_u32 s2, s2, 0x80
	s_addc_u32 s3, s3, 0
	s_cmpk_eq_i32 s2, 0x780
	s_mov_b32 s4, s5
	v_mfma_f32_16x16x32_bf16 v[8:11], v[212:215], v[216:219], v[8:11]
	v_mfma_f32_16x16x32_bf16 v[4:7], v[212:215], v[220:223], v[4:7]
	v_mfma_f32_16x16x32_bf16 v[0:3], v[212:215], v[224:227], v[0:3]
	v_mfma_f32_16x16x32_bf16 v[108:111], v[212:215], v[228:231], v[108:111]
	s_cbranch_scc0 .LBB0_1074
	s_add_i32 s2, 0, 0x10000
	v_add_u32_e32 v136, s2, v145
	v_add_u32_e32 v174, s2, v144
	v_add_u32_e32 v137, v136, v143
	v_add_u32_e32 v143, v174, v143
	s_waitcnt vmcnt(0)
	s_barrier
	ds_read_b128 v[128:131], v137 offset:38912
	ds_read_b128 v[132:135], v137 offset:36864
	ds_read_b128 v[146:149], v137 offset:34816
	ds_read_b128 v[150:153], v137 offset:32768
	ds_read_b128 v[154:157], v143 offset:6144
	ds_read_b128 v[158:161], v143 offset:4096
	ds_read_b128 v[170:173], v143 offset:2048
	ds_read_b128 v[178:181], v143
	s_waitcnt lgkmcnt(0)
	v_mfma_f32_16x16x32_bf16 v[124:127], v[178:181], v[150:153], v[124:127]
	v_mfma_f32_16x16x32_bf16 v[120:123], v[178:181], v[146:149], v[120:123]
	v_mfma_f32_16x16x32_bf16 v[116:119], v[178:181], v[132:135], v[116:119]
	v_mfma_f32_16x16x32_bf16 v[112:115], v[178:181], v[128:131], v[112:115]
	v_mfma_f32_16x16x32_bf16 v[104:107], v[170:173], v[150:153], v[104:107]
	v_mfma_f32_16x16x32_bf16 v[72:75], v[158:161], v[150:153], v[72:75]
	v_mfma_f32_16x16x32_bf16 v[64:67], v[158:161], v[146:149], v[64:67]
	v_mfma_f32_16x16x32_bf16 v[56:59], v[158:161], v[132:135], v[56:59]
	v_mfma_f32_16x16x32_bf16 v[48:51], v[158:161], v[128:131], v[48:51]
	v_mfma_f32_16x16x32_bf16 v[182:185], v[170:173], v[146:149], v[96:99]
	v_mfma_f32_16x16x32_bf16 v[186:189], v[170:173], v[132:135], v[88:91]
	v_mfma_f32_16x16x32_bf16 v[192:195], v[170:173], v[128:131], v[80:83]
	v_mfma_f32_16x16x32_bf16 v[150:153], v[154:157], v[150:153], v[40:43]
	v_mfma_f32_16x16x32_bf16 v[144:147], v[154:157], v[146:149], v[32:35]
	v_mfma_f32_16x16x32_bf16 v[132:135], v[154:157], v[132:135], v[24:27]
	v_mfma_f32_16x16x32_bf16 v[128:131], v[154:157], v[128:131], v[16:19]
	s_nop 2
	ds_read_b128 v[16:19], v137 offset:40960
	ds_read_b128 v[24:27], v137 offset:43008
	ds_read_b128 v[32:35], v137 offset:45056
	ds_read_b128 v[40:43], v137 offset:47104
	s_waitcnt lgkmcnt(0)
	v_mfma_f32_16x16x32_bf16 v[100:103], v[178:181], v[16:19], v[100:103]
	v_mfma_f32_16x16x32_bf16 v[92:95], v[178:181], v[24:27], v[92:95]
	v_mfma_f32_16x16x32_bf16 v[198:201], v[178:181], v[32:35], v[84:87]
	v_mfma_f32_16x16x32_bf16 v[76:79], v[178:181], v[40:43], v[76:79]
	v_mfma_f32_16x16x32_bf16 v[68:71], v[170:173], v[16:19], v[68:71]
	v_mfma_f32_16x16x32_bf16 v[60:63], v[170:173], v[24:27], v[60:63]
	v_mfma_f32_16x16x32_bf16 v[178:181], v[170:173], v[32:35], v[52:55]
	v_mfma_f32_16x16x32_bf16 v[44:47], v[170:173], v[40:43], v[44:47]
	v_mfma_f32_16x16x32_bf16 v[170:173], v[158:161], v[16:19], v[36:39]
	v_mfma_f32_16x16x32_bf16 v[204:207], v[158:161], v[24:27], v[28:31]
	v_mfma_f32_16x16x32_bf16 v[208:211], v[158:161], v[32:35], v[20:23]
	v_mfma_f32_16x16x32_bf16 v[158:161], v[158:161], v[40:43], v[12:15]
	v_mfma_f32_16x16x32_bf16 v[212:215], v[154:157], v[16:19], v[8:11]
	v_mfma_f32_16x16x32_bf16 v[216:219], v[154:157], v[24:27], v[4:7]
	v_mfma_f32_16x16x32_bf16 v[220:223], v[154:157], v[32:35], v[0:3]
	v_mfma_f32_16x16x32_bf16 v[154:157], v[154:157], v[40:43], v[108:111]
	s_nop 1
	v_add_u32_e32 v0, v174, v142
	v_add_u32_e32 v136, v136, v142
	ds_read_b128 v[108:111], v0
	ds_read_b128 v[224:227], v0 offset:2048
	ds_read_b128 v[228:231], v0 offset:4096
	ds_read_b128 v[232:235], v0 offset:6144
	ds_read_b128 v[0:3], v136 offset:32768
	ds_read_b128 v[4:7], v136 offset:34816
	ds_read_b128 v[236:239], v136 offset:36864
	ds_read_b128 v[240:243], v136 offset:38912
	s_waitcnt lgkmcnt(0)
	v_mfma_f32_16x16x32_bf16 v[88:91], v[108:111], v[0:3], v[124:127]
	v_mfma_f32_16x16x32_bf16 v[96:99], v[108:111], v[4:7], v[120:123]
	v_mfma_f32_16x16x32_bf16 v[80:83], v[108:111], v[236:239], v[116:119]
	v_mfma_f32_16x16x32_bf16 v[84:87], v[108:111], v[240:243], v[112:115]
	v_mfma_f32_16x16x32_bf16 v[40:43], v[224:227], v[0:3], v[104:107]
	v_mfma_f32_16x16x32_bf16 v[52:55], v[224:227], v[4:7], v[182:185]
	v_mfma_f32_16x16x32_bf16 v[32:35], v[224:227], v[236:239], v[186:189]
	v_mfma_f32_16x16x32_bf16 v[36:39], v[224:227], v[240:243], v[192:195]
	v_mfma_f32_16x16x32_bf16 v[24:27], v[228:231], v[0:3], v[72:75]
	v_mfma_f32_16x16x32_bf16 v[28:31], v[228:231], v[4:7], v[64:67]
	v_mfma_f32_16x16x32_bf16 v[16:19], v[228:231], v[236:239], v[56:59]
	v_mfma_f32_16x16x32_bf16 v[20:23], v[228:231], v[240:243], v[48:51]
	v_mfma_f32_16x16x32_bf16 v[8:11], v[232:235], v[0:3], v[150:153]
	v_mfma_f32_16x16x32_bf16 v[12:15], v[232:235], v[4:7], v[144:147]
	v_mfma_f32_16x16x32_bf16 v[0:3], v[232:235], v[236:239], v[132:135]
	v_mfma_f32_16x16x32_bf16 v[4:7], v[232:235], v[240:243], v[128:131]
	ds_read_b128 v[48:51], v136 offset:40960
	ds_read_b128 v[64:67], v136 offset:43008
	s_nop 0
	ds_read_b128 v[128:131], v136 offset:45056
	ds_read_b128 v[132:135], v136 offset:47104
	s_waitcnt lgkmcnt(0)
	v_mfma_f32_16x16x32_bf16 v[104:107], v[224:227], v[48:51], v[68:71]
	v_cmp_ne_u32_e32 vcc, 0, v138
	v_cmp_eq_u32_e64 s[2:3], 0, v138
	s_waitcnt vmcnt(0)
	v_lshl_or_b32 v68, v140, 2, v141
	v_lshl_add_u32 v69, v139, 2, 0
	v_mfma_f32_16x16x32_bf16 v[120:123], v[108:111], v[48:51], v[100:103]
	s_barrier
	v_mfma_f32_16x16x32_bf16 v[124:127], v[108:111], v[64:67], v[92:95]
	v_mfma_f32_16x16x32_bf16 v[112:115], v[108:111], v[128:131], v[198:201]
	v_mfma_f32_16x16x32_bf16 v[116:119], v[108:111], v[132:135], v[76:79]
	v_mfma_f32_16x16x32_bf16 v[108:111], v[224:227], v[64:67], v[60:63]
	v_mfma_f32_16x16x32_bf16 v[92:95], v[224:227], v[128:131], v[178:181]
	v_mfma_f32_16x16x32_bf16 v[100:103], v[224:227], v[132:135], v[44:47]
	s_nop 1
	v_lshl_add_u32 v178, v68, 9, v69
	v_add_u32_e32 v179, 0x400, v178
	v_add_u32_e32 v176, 0x2000, v178
	v_mfma_f32_16x16x32_bf16 v[56:59], v[228:231], v[48:51], v[170:173]
	v_add_u32_e32 v175, 0x2400, v178
	v_add_u32_e32 v174, 0x4000, v178
	v_mfma_f32_16x16x32_bf16 v[60:63], v[228:231], v[64:67], v[204:207]
	v_add_u32_e32 v173, 0x4400, v178
	v_add_u32_e32 v172, 0x6000, v178
	v_add_u32_e32 v171, 0x6400, v178
	v_mfma_f32_16x16x32_bf16 v[44:47], v[228:231], v[128:131], v[208:211]
	v_mfma_f32_16x16x32_bf16 v[72:75], v[228:231], v[132:135], v[158:161]
	v_mfma_f32_16x16x32_bf16 v[48:51], v[232:235], v[48:51], v[212:215]
	v_mfma_f32_16x16x32_bf16 v[64:67], v[232:235], v[64:67], v[216:219]
	v_mfma_f32_16x16x32_bf16 v[68:71], v[232:235], v[128:131], v[220:223]
	v_mfma_f32_16x16x32_bf16 v[76:79], v[232:235], v[132:135], v[154:157]
	s_and_saveexec_b64 s[4:5], s[2:3]
	s_cbranch_execz .LBB0_1077
	ds_write2_b32 v178, v88, v96 offset1:16
	ds_write2_b32 v178, v89, v97 offset0:128 offset1:144
	ds_write2_b32 v179, v90, v98 offset1:16
	ds_write2_b32 v179, v91, v99 offset0:128 offset1:144
	ds_write2_b32 v178, v80, v84 offset0:32 offset1:48
	ds_write2_b32 v178, v81, v85 offset0:160 offset1:176
	ds_write2_b32 v179, v82, v86 offset0:32 offset1:48
	ds_write2_b32 v179, v83, v87 offset0:160 offset1:176
	ds_write2_b32 v178, v120, v124 offset0:64 offset1:80
	ds_write2_b32 v178, v121, v125 offset0:192 offset1:208
	ds_write2_b32 v179, v122, v126 offset0:64 offset1:80
	ds_write2_b32 v179, v123, v127 offset0:192 offset1:208
	ds_write2_b32 v178, v112, v116 offset0:96 offset1:112
	ds_write2_b32 v178, v113, v117 offset0:224 offset1:240
	ds_write2_b32 v179, v114, v118 offset0:96 offset1:112
	ds_write2_b32 v179, v115, v119 offset0:224 offset1:240
	ds_write2_b32 v176, v40, v52 offset1:16
	ds_write2_b32 v176, v41, v53 offset0:128 offset1:144
	ds_write2_b32 v175, v42, v54 offset1:16
	ds_write2_b32 v175, v43, v55 offset0:128 offset1:144
	ds_write2_b32 v176, v32, v36 offset0:32 offset1:48
	ds_write2_b32 v176, v33, v37 offset0:160 offset1:176
	ds_write2_b32 v175, v34, v38 offset0:32 offset1:48
	ds_write2_b32 v175, v35, v39 offset0:160 offset1:176
	ds_write2_b32 v176, v104, v108 offset0:64 offset1:80
	ds_write2_b32 v176, v105, v109 offset0:192 offset1:208
	ds_write2_b32 v175, v106, v110 offset0:64 offset1:80
	ds_write2_b32 v175, v107, v111 offset0:192 offset1:208
	ds_write2_b32 v176, v92, v100 offset0:96 offset1:112
	ds_write2_b32 v176, v93, v101 offset0:224 offset1:240
	ds_write2_b32 v175, v94, v102 offset0:96 offset1:112
	ds_write2_b32 v175, v95, v103 offset0:224 offset1:240
	ds_write2_b32 v174, v24, v28 offset1:16
	ds_write2_b32 v174, v25, v29 offset0:128 offset1:144
	ds_write2_b32 v173, v26, v30 offset1:16
	ds_write2_b32 v173, v27, v31 offset0:128 offset1:144
	ds_write2_b32 v174, v16, v20 offset0:32 offset1:48
	ds_write2_b32 v174, v17, v21 offset0:160 offset1:176
	ds_write2_b32 v173, v18, v22 offset0:32 offset1:48
	ds_write2_b32 v173, v19, v23 offset0:160 offset1:176
	ds_write2_b32 v174, v56, v60 offset0:64 offset1:80
	ds_write2_b32 v174, v57, v61 offset0:192 offset1:208
	ds_write2_b32 v173, v58, v62 offset0:64 offset1:80
	ds_write2_b32 v173, v59, v63 offset0:192 offset1:208
	ds_write2_b32 v174, v44, v72 offset0:96 offset1:112
	ds_write2_b32 v174, v45, v73 offset0:224 offset1:240
	ds_write2_b32 v173, v46, v74 offset0:96 offset1:112
	ds_write2_b32 v173, v47, v75 offset0:224 offset1:240
	ds_write2_b32 v172, v8, v12 offset1:16
	ds_write2_b32 v172, v9, v13 offset0:128 offset1:144
	ds_write2_b32 v171, v10, v14 offset1:16
	ds_write2_b32 v171, v11, v15 offset0:128 offset1:144
	ds_write2_b32 v172, v0, v4 offset0:32 offset1:48
	ds_write2_b32 v172, v1, v5 offset0:160 offset1:176
	ds_write2_b32 v171, v2, v6 offset0:32 offset1:48
	ds_write2_b32 v171, v3, v7 offset0:160 offset1:176
	ds_write2_b32 v172, v48, v64 offset0:64 offset1:80
	ds_write2_b32 v172, v49, v65 offset0:192 offset1:208
	ds_write2_b32 v171, v50, v66 offset0:64 offset1:80
	ds_write2_b32 v171, v51, v67 offset0:192 offset1:208
	ds_write2_b32 v172, v68, v76 offset0:96 offset1:112
	ds_write2_b32 v172, v69, v77 offset0:224 offset1:240
	ds_write2_b32 v171, v70, v78 offset0:96 offset1:112
	ds_write2_b32 v171, v71, v79 offset0:224 offset1:240

.LBB0_1143:
	s_add_i32 s11, s10, 0x10000
	s_and_b32 s19, s11, 0x10000
	s_waitcnt vmcnt(0)
	s_barrier
	s_and_b32 s10, s10, 0x10000
	s_add_i32 s10, s10, 0
	v_add_u32_e32 v151, s10, v149
	v_add_u32_e32 v164, v151, v147
	ds_read_b128 v[152:155], v164
	ds_read_b128 v[156:159], v164 offset:2048
	ds_read_b128 v[160:163], v164 offset:4096
	ds_read_b128 v[164:167], v164 offset:6144
	v_add_u32_e32 v251, v151, v146
	v_add_u32_e32 v176, s10, v148
	v_add_u32_e32 v186, v176, v147
	ds_read_b128 v[168:171], v186 offset:32768
	ds_read_b128 v[172:175], v186 offset:34816
	ds_read_b128 v[178:181], v186 offset:36864
	ds_read_b128 v[182:185], v186 offset:38912
	v_add_u32_e32 v250, v176, v146
	s_waitcnt lgkmcnt(0)
	v_mfma_f32_16x16x32_bf16 v[124:127], v[152:155], v[168:171], v[124:127]
	ds_read_b128 v[212:215], v186 offset:40960
	v_mfma_f32_16x16x32_bf16 v[120:123], v[152:155], v[172:175], v[120:123]
	ds_read_b128 v[216:219], v186 offset:43008
	v_mfma_f32_16x16x32_bf16 v[116:119], v[152:155], v[178:181], v[116:119]
	ds_read_b128 v[220:223], v186 offset:45056
	v_mfma_f32_16x16x32_bf16 v[112:115], v[152:155], v[182:185], v[112:115]
	ds_read_b128 v[224:227], v186 offset:47104
	v_mfma_f32_16x16x32_bf16 v[104:107], v[156:159], v[168:171], v[104:107]
	ds_read_b128 v[192:195], v251
	v_mfma_f32_16x16x32_bf16 v[96:99], v[156:159], v[172:175], v[96:99]
	ds_read_b128 v[198:201], v251 offset:2048
	v_mfma_f32_16x16x32_bf16 v[88:91], v[156:159], v[178:181], v[88:91]
	ds_read_b128 v[204:207], v251 offset:4096
	v_mfma_f32_16x16x32_bf16 v[80:83], v[156:159], v[182:185], v[80:83]
	ds_read_b128 v[208:211], v251 offset:6144
	v_mfma_f32_16x16x32_bf16 v[72:75], v[160:163], v[168:171], v[72:75]
	v_mfma_f32_16x16x32_bf16 v[64:67], v[160:163], v[172:175], v[64:67]
	v_mfma_f32_16x16x32_bf16 v[56:59], v[160:163], v[178:181], v[56:59]
	v_mfma_f32_16x16x32_bf16 v[48:51], v[160:163], v[182:185], v[48:51]
	v_mfma_f32_16x16x32_bf16 v[40:43], v[164:167], v[168:171], v[40:43]
	v_mfma_f32_16x16x32_bf16 v[32:35], v[164:167], v[172:175], v[32:35]
	v_mfma_f32_16x16x32_bf16 v[24:27], v[164:167], v[178:181], v[24:27]
	v_mfma_f32_16x16x32_bf16 v[16:19], v[164:167], v[182:185], v[16:19]
	s_waitcnt lgkmcnt(4)
	v_mfma_f32_16x16x32_bf16 v[100:103], v[152:155], v[212:215], v[100:103]
	v_add_u32_e32 v254, s19, v150
	v_add_u32_e32 v228, 0x2000, v254
	v_mfma_f32_16x16x32_bf16 v[92:95], v[152:155], v[216:219], v[92:95]
	v_readfirstlane_b32 s19, v254
	v_lshl_add_u64 v[188:189], v[128:129], 0, s[2:3]
	v_mfma_f32_16x16x32_bf16 v[84:87], v[152:155], v[220:223], v[84:87]
	ds_read_b128 v[168:171], v250 offset:32768
	s_mov_b32 m0, s19
	v_readfirstlane_b32 s19, v228
	v_mfma_f32_16x16x32_bf16 v[76:79], v[152:155], v[224:227], v[76:79]
	ds_read_b128 v[172:175], v250 offset:34816
	v_add_u32_e32 v228, 0x4000, v254
	global_load_lds_dwordx4 v[188:189], off
	v_mfma_f32_16x16x32_bf16 v[68:71], v[156:159], v[212:215], v[68:71]
	ds_read_b128 v[178:181], v250 offset:36864
	v_lshl_add_u64 v[188:189], v[130:131], 0, s[2:3]
	s_mov_b32 m0, s19
	v_mfma_f32_16x16x32_bf16 v[60:63], v[156:159], v[216:219], v[60:63]
	ds_read_b128 v[182:185], v250 offset:38912
	v_readfirstlane_b32 s19, v228
	v_add_u32_e32 v228, 0x6000, v254
	v_mfma_f32_16x16x32_bf16 v[52:55], v[156:159], v[220:223], v[52:55]
	global_load_lds_dwordx4 v[188:189], off
	v_lshl_add_u64 v[188:189], v[132:133], 0, s[2:3]
	v_mfma_f32_16x16x32_bf16 v[44:47], v[156:159], v[224:227], v[44:47]
	s_mov_b32 m0, s19
	v_readfirstlane_b32 s19, v228
	v_mfma_f32_16x16x32_bf16 v[36:39], v[160:163], v[212:215], v[36:39]
	global_load_lds_dwordx4 v[188:189], off
	v_lshl_add_u64 v[188:189], v[134:135], 0, s[2:3]
	v_mfma_f32_16x16x32_bf16 v[28:31], v[160:163], v[216:219], v[28:31]
	s_mov_b32 m0, s19
	v_add_u32_e32 v253, 0x8000, v254
	v_mfma_f32_16x16x32_bf16 v[20:23], v[160:163], v[220:223], v[20:23]
	global_load_lds_dwordx4 v[188:189], off
	v_lshl_add_u64 v[188:189], v[136:137], 0, s[2:3]
	v_mfma_f32_16x16x32_bf16 v[12:15], v[160:163], v[224:227], v[12:15]
	s_mov_b64 s[20:21], 0x1320080
	v_readfirstlane_b32 s19, v253
	v_mfma_f32_16x16x32_bf16 v[8:11], v[164:167], v[212:215], v[8:11]
	v_add_u32_e32 v253, 0xa000, v254
	v_lshl_add_u64 v[228:229], v[188:189], 0, s[20:21]
	v_mfma_f32_16x16x32_bf16 v[4:7], v[164:167], v[216:219], v[4:7]
	s_mov_b32 m0, s19
	s_mov_b64 s[20:21], 0x1378080
	v_mfma_f32_16x16x32_bf16 v[0:3], v[164:167], v[220:223], v[0:3]
	v_readfirstlane_b32 s19, v253
	v_add_u32_e32 v253, 0xc000, v254
	v_mfma_f32_16x16x32_bf16 v[108:111], v[164:167], v[224:227], v[108:111]
	global_load_lds_dwordx4 v[228:229], off
	v_lshl_add_u64 v[228:229], v[188:189], 0, s[20:21]
	s_waitcnt lgkmcnt(0)
	v_mfma_f32_16x16x32_bf16 v[124:127], v[192:195], v[168:171], v[124:127]
	ds_read_b128 v[212:215], v250 offset:40960
	s_mov_b32 m0, s19
	s_mov_b64 s[20:21], 0x13d0080
	v_mfma_f32_16x16x32_bf16 v[120:123], v[192:195], v[172:175], v[120:123]
	ds_read_b128 v[216:219], v250 offset:43008
	v_readfirstlane_b32 s19, v253
	v_add_u32_e32 v254, 0xe000, v254
	v_mfma_f32_16x16x32_bf16 v[116:119], v[192:195], v[178:181], v[116:119]
	ds_read_b128 v[220:223], v250 offset:45056
	global_load_lds_dwordx4 v[228:229], off
	v_lshl_add_u64 v[228:229], v[188:189], 0, s[20:21]
	v_mfma_f32_16x16x32_bf16 v[112:115], v[192:195], v[182:185], v[112:115]
	ds_read_b128 v[224:227], v250 offset:47104
	s_mov_b32 m0, s19
	s_mov_b64 s[20:21], 0x1428080
	v_mfma_f32_16x16x32_bf16 v[104:107], v[198:201], v[168:171], v[104:107]
	v_readfirstlane_b32 s19, v254
	global_load_lds_dwordx4 v[228:229], off
	v_mfma_f32_16x16x32_bf16 v[96:99], v[198:201], v[172:175], v[96:99]
	v_lshl_add_u64 v[188:189], v[188:189], 0, s[20:21]
	s_mov_b32 m0, s19
	v_mfma_f32_16x16x32_bf16 v[88:91], v[198:201], v[178:181], v[88:91]
	global_load_lds_dwordx4 v[188:189], off
	v_mfma_f32_16x16x32_bf16 v[80:83], v[198:201], v[182:185], v[80:83]
	v_mfma_f32_16x16x32_bf16 v[72:75], v[204:207], v[168:171], v[72:75]
	v_mfma_f32_16x16x32_bf16 v[64:67], v[204:207], v[172:175], v[64:67]
	v_mfma_f32_16x16x32_bf16 v[56:59], v[204:207], v[178:181], v[56:59]
	v_mfma_f32_16x16x32_bf16 v[48:51], v[204:207], v[182:185], v[48:51]
	v_mfma_f32_16x16x32_bf16 v[40:43], v[208:211], v[168:171], v[40:43]
	v_mfma_f32_16x16x32_bf16 v[32:35], v[208:211], v[172:175], v[32:35]
	v_mfma_f32_16x16x32_bf16 v[24:27], v[208:211], v[178:181], v[24:27]
	v_mfma_f32_16x16x32_bf16 v[16:19], v[208:211], v[182:185], v[16:19]
	s_waitcnt lgkmcnt(0)
	v_mfma_f32_16x16x32_bf16 v[100:103], v[192:195], v[212:215], v[100:103]
	v_mfma_f32_16x16x32_bf16 v[92:95], v[192:195], v[216:219], v[92:95]
	v_mfma_f32_16x16x32_bf16 v[84:87], v[192:195], v[220:223], v[84:87]
	v_mfma_f32_16x16x32_bf16 v[76:79], v[192:195], v[224:227], v[76:79]
	v_mfma_f32_16x16x32_bf16 v[68:71], v[198:201], v[212:215], v[68:71]
	v_mfma_f32_16x16x32_bf16 v[60:63], v[198:201], v[216:219], v[60:63]
	v_mfma_f32_16x16x32_bf16 v[52:55], v[198:201], v[220:223], v[52:55]
	v_mfma_f32_16x16x32_bf16 v[44:47], v[198:201], v[224:227], v[44:47]
	v_mfma_f32_16x16x32_bf16 v[36:39], v[204:207], v[212:215], v[36:39]
	v_mfma_f32_16x16x32_bf16 v[28:31], v[204:207], v[216:219], v[28:31]
	v_mfma_f32_16x16x32_bf16 v[20:23], v[204:207], v[220:223], v[20:23]
	v_mfma_f32_16x16x32_bf16 v[12:15], v[204:207], v[224:227], v[12:15]
	s_add_u32 s2, s2, 0x80
	s_addc_u32 s3, s3, 0
	s_cmpk_eq_i32 s2, 0x1580
	s_mov_b32 s10, s11
	v_mfma_f32_16x16x32_bf16 v[8:11], v[208:211], v[212:215], v[8:11]
	v_mfma_f32_16x16x32_bf16 v[4:7], v[208:211], v[216:219], v[4:7]
	v_mfma_f32_16x16x32_bf16 v[0:3], v[208:211], v[220:223], v[0:3]
	v_mfma_f32_16x16x32_bf16 v[108:111], v[208:211], v[224:227], v[108:111]
	s_cbranch_scc0 .LBB0_1143
	s_add_i32 s2, 0, 0x10000
	v_add_u32_e32 v136, s2, v149
	v_add_u32_e32 v137, v136, v147
	s_waitcnt vmcnt(0)
	s_barrier
	ds_read_b128 v[128:131], v137
	ds_read_b128 v[132:135], v137 offset:2048
	ds_read_b128 v[150:153], v137 offset:4096
	ds_read_b128 v[154:157], v137 offset:6144
	v_add_u32_e32 v137, s2, v148
	v_add_u32_e32 v147, v137, v147
	ds_read_b128 v[158:161], v147 offset:32768
	ds_read_b128 v[162:165], v147 offset:34816
	ds_read_b128 v[166:169], v147 offset:36864
	ds_read_b128 v[170:173], v147 offset:38912
	s_waitcnt lgkmcnt(0)
	v_mfma_f32_16x16x32_bf16 v[124:127], v[128:131], v[158:161], v[124:127]
	v_mfma_f32_16x16x32_bf16 v[120:123], v[128:131], v[162:165], v[120:123]
	v_mfma_f32_16x16x32_bf16 v[116:119], v[128:131], v[166:169], v[116:119]
	v_mfma_f32_16x16x32_bf16 v[112:115], v[128:131], v[170:173], v[112:115]
	v_mfma_f32_16x16x32_bf16 v[104:107], v[132:135], v[158:161], v[104:107]
	v_mfma_f32_16x16x32_bf16 v[72:75], v[150:153], v[158:161], v[72:75]
	v_mfma_f32_16x16x32_bf16 v[64:67], v[150:153], v[162:165], v[64:67]
	v_mfma_f32_16x16x32_bf16 v[56:59], v[150:153], v[166:169], v[56:59]
	v_mfma_f32_16x16x32_bf16 v[48:51], v[150:153], v[170:173], v[48:51]
	v_mfma_f32_16x16x32_bf16 v[178:181], v[132:135], v[162:165], v[96:99]
	v_mfma_f32_16x16x32_bf16 v[182:185], v[132:135], v[166:169], v[88:91]
	v_mfma_f32_16x16x32_bf16 v[186:189], v[132:135], v[170:173], v[80:83]
	v_mfma_f32_16x16x32_bf16 v[158:161], v[154:157], v[158:161], v[40:43]
	v_mfma_f32_16x16x32_bf16 v[162:165], v[154:157], v[162:165], v[32:35]
	v_mfma_f32_16x16x32_bf16 v[166:169], v[154:157], v[166:169], v[24:27]
	v_mfma_f32_16x16x32_bf16 v[170:173], v[154:157], v[170:173], v[16:19]
	s_nop 2
	ds_read_b128 v[16:19], v147 offset:40960
	ds_read_b128 v[24:27], v147 offset:43008
	ds_read_b128 v[32:35], v147 offset:45056
	ds_read_b128 v[40:43], v147 offset:47104
	s_waitcnt lgkmcnt(0)
	v_mfma_f32_16x16x32_bf16 v[100:103], v[128:131], v[16:19], v[100:103]
	v_mfma_f32_16x16x32_bf16 v[92:95], v[128:131], v[24:27], v[92:95]
	v_mfma_f32_16x16x32_bf16 v[192:195], v[128:131], v[32:35], v[84:87]
	v_mfma_f32_16x16x32_bf16 v[76:79], v[128:131], v[40:43], v[76:79]
	v_mfma_f32_16x16x32_bf16 v[68:71], v[132:135], v[16:19], v[68:71]
	v_mfma_f32_16x16x32_bf16 v[60:63], v[132:135], v[24:27], v[60:63]
	v_mfma_f32_16x16x32_bf16 v[128:131], v[132:135], v[32:35], v[52:55]
	v_mfma_f32_16x16x32_bf16 v[44:47], v[132:135], v[40:43], v[44:47]
	v_mfma_f32_16x16x32_bf16 v[132:135], v[150:153], v[16:19], v[36:39]
	v_mfma_f32_16x16x32_bf16 v[198:201], v[150:153], v[24:27], v[28:31]
	v_mfma_f32_16x16x32_bf16 v[204:207], v[150:153], v[32:35], v[20:23]
	v_mfma_f32_16x16x32_bf16 v[148:151], v[150:153], v[40:43], v[12:15]
	v_mfma_f32_16x16x32_bf16 v[208:211], v[154:157], v[16:19], v[8:11]
	v_mfma_f32_16x16x32_bf16 v[212:215], v[154:157], v[24:27], v[4:7]
	v_mfma_f32_16x16x32_bf16 v[216:219], v[154:157], v[32:35], v[0:3]
	v_mfma_f32_16x16x32_bf16 v[154:157], v[154:157], v[40:43], v[108:111]
	s_nop 1
	v_add_u32_e32 v0, v136, v146
	v_add_u32_e32 v136, v137, v146
	ds_read_b128 v[108:111], v0
	ds_read_b128 v[220:223], v0 offset:2048
	ds_read_b128 v[224:227], v0 offset:4096
	ds_read_b128 v[228:231], v0 offset:6144
	ds_read_b128 v[0:3], v136 offset:32768
	ds_read_b128 v[4:7], v136 offset:34816
	ds_read_b128 v[232:235], v136 offset:36864
	ds_read_b128 v[236:239], v136 offset:38912
	s_waitcnt lgkmcnt(0)
	v_mfma_f32_16x16x32_bf16 v[88:91], v[108:111], v[0:3], v[124:127]
	v_mfma_f32_16x16x32_bf16 v[96:99], v[108:111], v[4:7], v[120:123]
	v_mfma_f32_16x16x32_bf16 v[80:83], v[108:111], v[232:235], v[116:119]
	v_mfma_f32_16x16x32_bf16 v[84:87], v[108:111], v[236:239], v[112:115]
	v_mfma_f32_16x16x32_bf16 v[40:43], v[220:223], v[0:3], v[104:107]
	v_mfma_f32_16x16x32_bf16 v[52:55], v[220:223], v[4:7], v[178:181]
	v_mfma_f32_16x16x32_bf16 v[32:35], v[220:223], v[232:235], v[182:185]
	v_mfma_f32_16x16x32_bf16 v[36:39], v[220:223], v[236:239], v[186:189]
	v_mfma_f32_16x16x32_bf16 v[24:27], v[224:227], v[0:3], v[72:75]
	v_mfma_f32_16x16x32_bf16 v[28:31], v[224:227], v[4:7], v[64:67]
	v_mfma_f32_16x16x32_bf16 v[16:19], v[224:227], v[232:235], v[56:59]
	v_mfma_f32_16x16x32_bf16 v[20:23], v[224:227], v[236:239], v[48:51]
	v_mfma_f32_16x16x32_bf16 v[8:11], v[228:231], v[0:3], v[158:161]
	v_mfma_f32_16x16x32_bf16 v[12:15], v[228:231], v[4:7], v[162:165]
	v_mfma_f32_16x16x32_bf16 v[0:3], v[228:231], v[232:235], v[166:169]
	v_mfma_f32_16x16x32_bf16 v[4:7], v[228:231], v[236:239], v[170:173]
	ds_read_b128 v[48:51], v136 offset:40960
	ds_read_b128 v[64:67], v136 offset:43008
	ds_read_b128 v[158:161], v136 offset:45056
	ds_read_b128 v[162:165], v136 offset:47104
	s_waitcnt lgkmcnt(0)
	v_mfma_f32_16x16x32_bf16 v[104:107], v[220:223], v[48:51], v[68:71]
	v_cmp_ne_u32_e32 vcc, 0, v138
	v_cmp_eq_u32_e64 s[2:3], 0, v138
	s_waitcnt vmcnt(0)
	v_lshl_or_b32 v68, v140, 2, v141
	v_lshl_add_u32 v69, v139, 2, 0
	v_mfma_f32_16x16x32_bf16 v[120:123], v[108:111], v[48:51], v[100:103]
	v_lshl_add_u32 v152, v68, 9, v69
	v_add_u32_e32 v153, 0x400, v152
	v_add_u32_e32 v147, 0x6000, v152
	v_mfma_f32_16x16x32_bf16 v[124:127], v[108:111], v[64:67], v[92:95]
	v_add_u32_e32 v146, 0x6400, v152
	s_barrier
	v_mfma_f32_16x16x32_bf16 v[112:115], v[108:111], v[158:161], v[192:195]
	v_mfma_f32_16x16x32_bf16 v[116:119], v[108:111], v[162:165], v[76:79]
	v_mfma_f32_16x16x32_bf16 v[108:111], v[220:223], v[64:67], v[60:63]
	v_mfma_f32_16x16x32_bf16 v[92:95], v[220:223], v[158:161], v[128:131]
	v_mfma_f32_16x16x32_bf16 v[100:103], v[220:223], v[162:165], v[44:47]
	v_mfma_f32_16x16x32_bf16 v[56:59], v[224:227], v[48:51], v[132:135]
	v_mfma_f32_16x16x32_bf16 v[60:63], v[224:227], v[64:67], v[198:201]
	v_mfma_f32_16x16x32_bf16 v[44:47], v[224:227], v[158:161], v[204:207]
	v_mfma_f32_16x16x32_bf16 v[72:75], v[224:227], v[162:165], v[148:151]
	v_mfma_f32_16x16x32_bf16 v[48:51], v[228:231], v[48:51], v[208:211]
	s_nop 1
	v_add_u32_e32 v151, 0x2000, v152
	v_add_u32_e32 v150, 0x2400, v152
	v_add_u32_e32 v149, 0x4000, v152
	v_mfma_f32_16x16x32_bf16 v[64:67], v[228:231], v[64:67], v[212:215]
	v_add_u32_e32 v148, 0x4400, v152
	v_mfma_f32_16x16x32_bf16 v[68:71], v[228:231], v[158:161], v[216:219]
	v_mfma_f32_16x16x32_bf16 v[76:79], v[228:231], v[162:165], v[154:157]
	s_and_saveexec_b64 s[10:11], s[2:3]
	s_cbranch_execz .LBB0_1146
	ds_write2_b32 v152, v88, v96 offset1:16
	ds_write2_b32 v152, v89, v97 offset0:128 offset1:144
	ds_write2_b32 v153, v90, v98 offset1:16
	ds_write2_b32 v153, v91, v99 offset0:128 offset1:144
	ds_write2_b32 v152, v80, v84 offset0:32 offset1:48
	ds_write2_b32 v152, v81, v85 offset0:160 offset1:176
	ds_write2_b32 v153, v82, v86 offset0:32 offset1:48
	ds_write2_b32 v153, v83, v87 offset0:160 offset1:176
	ds_write2_b32 v152, v120, v124 offset0:64 offset1:80
	ds_write2_b32 v152, v121, v125 offset0:192 offset1:208
	ds_write2_b32 v153, v122, v126 offset0:64 offset1:80
	ds_write2_b32 v153, v123, v127 offset0:192 offset1:208
	ds_write2_b32 v152, v112, v116 offset0:96 offset1:112
	ds_write2_b32 v152, v113, v117 offset0:224 offset1:240
	ds_write2_b32 v153, v114, v118 offset0:96 offset1:112
	ds_write2_b32 v153, v115, v119 offset0:224 offset1:240
	ds_write2_b32 v151, v40, v52 offset1:16
	ds_write2_b32 v151, v41, v53 offset0:128 offset1:144
	ds_write2_b32 v150, v42, v54 offset1:16
	ds_write2_b32 v150, v43, v55 offset0:128 offset1:144
	ds_write2_b32 v151, v32, v36 offset0:32 offset1:48
	ds_write2_b32 v151, v33, v37 offset0:160 offset1:176
	ds_write2_b32 v150, v34, v38 offset0:32 offset1:48
	ds_write2_b32 v150, v35, v39 offset0:160 offset1:176
	ds_write2_b32 v151, v104, v108 offset0:64 offset1:80
	ds_write2_b32 v151, v105, v109 offset0:192 offset1:208
	ds_write2_b32 v150, v106, v110 offset0:64 offset1:80
	ds_write2_b32 v150, v107, v111 offset0:192 offset1:208
	ds_write2_b32 v151, v92, v100 offset0:96 offset1:112
	ds_write2_b32 v151, v93, v101 offset0:224 offset1:240
	ds_write2_b32 v150, v94, v102 offset0:96 offset1:112
	ds_write2_b32 v150, v95, v103 offset0:224 offset1:240
	ds_write2_b32 v149, v24, v28 offset1:16
	ds_write2_b32 v149, v25, v29 offset0:128 offset1:144
	ds_write2_b32 v148, v26, v30 offset1:16
	ds_write2_b32 v148, v27, v31 offset0:128 offset1:144
	ds_write2_b32 v149, v16, v20 offset0:32 offset1:48
	ds_write2_b32 v149, v17, v21 offset0:160 offset1:176
	ds_write2_b32 v148, v18, v22 offset0:32 offset1:48
	ds_write2_b32 v148, v19, v23 offset0:160 offset1:176
	ds_write2_b32 v149, v56, v60 offset0:64 offset1:80
	ds_write2_b32 v149, v57, v61 offset0:192 offset1:208
	ds_write2_b32 v148, v58, v62 offset0:64 offset1:80
	ds_write2_b32 v148, v59, v63 offset0:192 offset1:208
	ds_write2_b32 v149, v44, v72 offset0:96 offset1:112
	ds_write2_b32 v149, v45, v73 offset0:224 offset1:240
	ds_write2_b32 v148, v46, v74 offset0:96 offset1:112
	ds_write2_b32 v148, v47, v75 offset0:224 offset1:240
	ds_write2_b32 v147, v8, v12 offset1:16
	ds_write2_b32 v147, v9, v13 offset0:128 offset1:144
	ds_write2_b32 v146, v10, v14 offset1:16
	ds_write2_b32 v146, v11, v15 offset0:128 offset1:144
	ds_write2_b32 v147, v0, v4 offset0:32 offset1:48
	ds_write2_b32 v147, v1, v5 offset0:160 offset1:176
	ds_write2_b32 v146, v2, v6 offset0:32 offset1:48
	ds_write2_b32 v146, v3, v7 offset0:160 offset1:176
	ds_write2_b32 v147, v48, v64 offset0:64 offset1:80
	ds_write2_b32 v147, v49, v65 offset0:192 offset1:208
	ds_write2_b32 v146, v50, v66 offset0:64 offset1:80
	ds_write2_b32 v146, v51, v67 offset0:192 offset1:208
	ds_write2_b32 v147, v68, v76 offset0:96 offset1:112
	ds_write2_b32 v147, v69, v77 offset0:224 offset1:240
	ds_write2_b32 v146, v70, v78 offset0:96 offset1:112
	ds_write2_b32 v146, v71, v79 offset0:224 offset1:240
